# K-tile LDS swizzle row&15 (conflict-free QK reads) + dsa_select two accumulator sets + dsa_select round prologue loads issued together
# baseline (speedup 1.0000x reference)
; #define GAS __attribute__((address_space(1)))
; #define LAS __attribute__((address_space(3)))
; __device__ __forceinline__ int crow(int r, int hi) { return (r & 3) + 8 * (r >> 2) + 4 * hi; }
; __device__ __forceinline__ int crow(int r, int hi) { return (r & 3) + 8 * (r >> 2) + 4 * hi; }
; #define DS_LOAD(R, tl) do { const bf16* s_ = kib + (size_t)((tl) * KT + p0k) * IDX_D + p0c * 8; R##0 = *(const GAS v4u*)s_; R##1 = *(const GAS v4u*)(s_ + 64 * IDX_D); R##2 = *(const GAS v4u*)(s_ + 128 * IDX_D); R##3 = *(const GAS v4u*)(s_ + 192 * IDX_D); } while (0)
; #define DS_WRITE(R, bf) do { LAS unsigned char* d_ = L + OFF_KI + (bf) * SZ_KI + p0k * KSTR + p0c * 16; *(LAS v4u*)d_ = R##0; *(LAS v4u*)(d_ + 64 * KSTR) = R##1; *(LAS v4u*)(d_ + 128 * KSTR) = R##2; *(LAS v4u*)(d_ + 192 * KSTR) = R##3; } while (0)
; __device__ __forceinline__ void dsa_select_phase(Frame& F) {
;     ...
;         bf16x8 aq[4]; float wv[16];
; #pragma unroll
;         for (int ks = 0; ks < 4; ++ks) aq[ks] = *(const GAS bf16x8*)(PROJ + row * DINM + O_IQ + r32 * IDX_D + 16 * ks + 8 * hi);
; #pragma unroll
;         for (int r = 0; r < 16; ++r) wv[r] = WI[row * IDX_H + crow(r, hi)];
;         const int ntile = (t0 + G - 1) / KT + 1;
;         const bf16* kib = KI + (size_t)b * T * IDX_D;
;         v4u sa0, sa1, sa2, sa3, sb0, sb1, sb2, sb3;
;         const int p0k = tid >> 3, p0c = tid & 7;
;     ...
;         __syncthreads();
;         if (tid < G * CNT_W) cnt_all[tid] = 0u;
;         ((LAS unsigned*)(L + OFF_SEL))[tid] = 0u;
;         DS_LOAD(sa, 0); if (ntile > 1) DS_LOAD(sb, 1);
;         DS_WRITE(sa, 0);
;         __syncthreads();
.LBB0_338:
	s_bitcmp0_b32 s61, 0
	s_mul_i32 s14, s61, s82
	s_cselect_b32 s62, s63, s65
	s_add_i32 s14, s62, s14
	s_cmpk_gt_i32 s14, 0x7ff
	s_mov_b32 s24, 2
	s_cbranch_scc1 .LBB0_553
	s_lshl_b32 s15, s14, 1
	s_and_b32 s15, s15, -4
	s_sub_i32 s18, s31, s15
	s_add_i32 s19, s18, 0xffc
	s_lshl_b32 s14, s14, 12
	s_and_b32 s24, s14, 0x1000
	s_ashr_i32 s14, s19, 31
	s_add_u32 s26, s19, s24
	s_addc_u32 s27, s14, 0
	s_sub_i32 s28, 0xfff, s15
	s_cmpk_lt_i32 s28, 0x100
	s_mov_b64 s[14:15], -1
	s_cbranch_scc1 .LBB0_549
	s_mul_i32 s14, s27, 0x6000
	s_mul_hi_u32 s15, s26, 0x6000
	s_add_i32 s15, s15, s14
	s_mul_i32 s14, s26, 0x6000
	s_add_u32 s14, s90, s14
	s_addc_u32 s15, s91, s15
	v_mov_b32_e32 v131, v1
	v_lshl_add_u64 v[2:3], s[14:15], 0, v[130:131]
	v_lshl_add_u64 v[2:3], v[114:115], 1, v[2:3]
	s_mov_b64 s[14:15], 0x3c905000
	v_lshl_add_u64 v[4:5], v[2:3], 0, s[14:15]
	s_mov_b32 s14, 0x3c905000
	v_add_co_u32_e32 v2, vcc, s14, v2
	s_lshl_b64 s[14:15], s[26:27], 7
	s_nop 0
	v_addc_co_u32_e32 v3, vcc, 0, v3, vcc
	global_load_dwordx4 v[18:21], v[4:5], off offset:32
	global_load_dwordx4 v[22:25], v[4:5], off offset:64
	global_load_dwordx4 v[26:29], v[2:3], off
	global_load_dwordx4 v[30:33], v[4:5], off offset:96
	v_lshl_add_u64 v[2:3], v[128:129], 0, s[14:15]
	flat_load_dwordx4 v[34:37], v[2:3]
	flat_load_dwordx4 v[38:41], v[2:3] offset:32
	flat_load_dwordx4 v[42:45], v[2:3] offset:64
	flat_load_dwordx4 v[46:49], v[2:3] offset:96
	s_lshr_b32 s28, s28, 8
	s_lshl_b32 s14, s24, 7
	s_add_u32 s14, s41, s14
	v_readlane_b32 s15, v255, 24
	s_addc_u32 s15, s15, 0
	v_mov_b32_e32 v133, v1
	v_lshl_add_u64 v[2:3], s[14:15], 0, v[118:119]
	v_lshl_add_u64 v[2:3], v[2:3], 0, v[132:133]
	s_movk_i32 s29, 0x2000
	v_add_co_u32_e32 v4, vcc, s29, v2
	s_movk_i32 s34, 0x4000
	s_nop 0
	v_addc_co_u32_e32 v5, vcc, 0, v3, vcc
	global_load_dwordx4 v[50:53], v[2:3], off
	global_load_dwordx4 v[54:57], v[4:5], off
	v_add_co_u32_e32 v4, vcc, s34, v2
	s_movk_i32 s24, 0x6000
	s_nop 0
	v_addc_co_u32_e32 v5, vcc, 0, v3, vcc
	v_add_co_u32_e32 v2, vcc, s24, v2
	v_mov_b32_e32 v0, 0xff61b1e6
	s_nop 0
	v_addc_co_u32_e32 v3, vcc, 0, v3, vcc
	global_load_dwordx4 v[58:61], v[4:5], off
	global_load_dwordx4 v[62:65], v[2:3], off
	v_lshl_add_u64 v[2:3], s[14:15], 0, v[120:121]
	v_lshl_add_u64 v[2:3], v[2:3], 0, v[132:133]
	v_add_co_u32_e32 v4, vcc, s24, v2
	v_mov_b32_e32 v131, 0x7f61b1e6
	s_nop 0
	v_addc_co_u32_e32 v5, vcc, 0, v3, vcc
	v_add_co_u32_e32 v6, vcc, s34, v2
	s_mov_b32 s34, 3
	s_nop 0
	v_addc_co_u32_e32 v7, vcc, 0, v3, vcc
	v_add_co_u32_e32 v8, vcc, s29, v2
	s_mov_b32 s29, 0
	s_nop 0
	v_addc_co_u32_e32 v9, vcc, 0, v3, vcc
	global_load_dwordx4 v[74:77], v[4:5], off
	global_load_dwordx4 v[66:69], v[2:3], off
	global_load_dwordx4 v[78:81], v[6:7], off
	global_load_dwordx4 v[70:73], v[8:9], off
	v_lshl_add_u64 v[134:135], s[14:15], 0, v[132:133]
	v_mov_b32_e32 v133, v145
	s_barrier
	s_mov_b64 s[14:15], exec
	v_readlane_b32 s98, v255, 22
	v_readlane_b32 s99, v255, 23
	s_and_b64 s[98:99], s[14:15], s[98:99]
	s_mov_b64 exec, s[98:99]
	ds_write_b32 v136, v1
	s_or_b64 exec, exec, s[14:15]
	ds_write_b32 v137, v1
	s_waitcnt vmcnt(0)
	ds_write_b128 v152, v[50:53]
	ds_write_b128 v152, v[54:57] offset:9216
	ds_write_b128 v152, v[58:61] offset:18432
	ds_write_b128 v152, v[62:65] offset:27648
	s_waitcnt lgkmcnt(0)
	s_barrier
	s_branch .LBB0_345

.LBB0_347:
	ds_read_b128 v[2:5], v139 offset:0
	ds_read_b128 v[154:157], v139 offset:32
	ds_read_b128 v[158:161], v139 offset:64
	ds_read_b128 v[162:165], v139 offset:0x60
	ds_read_b128 v[166:169], v139 offset:0x2400
	ds_read_b128 v[170:173], v139 offset:0x2420
	ds_read_b128 v[174:177], v139 offset:0x2440
	ds_read_b128 v[178:181], v139 offset:0x2460
	ds_read_b128 v[110:113], v139 offset:0x4800
	ds_read_b128 v[106:109], v139 offset:0x4820
	ds_read_b128 v[102:105], v139 offset:0x4840
	ds_read_b128 v[98:101], v139 offset:0x4860
	ds_read_b128 v[94:97], v139 offset:0x6c00
	ds_read_b128 v[90:93], v139 offset:0x6c20
	ds_read_b128 v[86:89], v139 offset:0x6c40
	ds_read_b128 v[82:85], v139 offset:0x6c60
	s_waitcnt lgkmcnt(12)
	v_mfma_f32_32x32x16_bf16 v[2:17], v[26:29], v[2:5], 0
	v_mfma_f32_32x32x16_bf16 v[2:17], v[18:21], v[154:157], v[2:17]
	v_mfma_f32_32x32x16_bf16 v[2:17], v[22:25], v[158:161], v[2:17]
	v_mfma_f32_32x32x16_bf16 v[2:17], v[30:33], v[162:165], v[2:17]
	s_waitcnt lgkmcnt(8)
	v_mfma_f32_32x32x16_bf16 v[184:199], v[26:29], v[166:169], 0
	v_mfma_f32_32x32x16_bf16 v[184:199], v[18:21], v[170:173], v[184:199]
	v_mfma_f32_32x32x16_bf16 v[184:199], v[22:25], v[174:177], v[184:199]
	v_mfma_f32_32x32x16_bf16 v[184:199], v[30:33], v[178:181], v[184:199]
	s_nop 6
	v_max_i32_e32 v2, 0, v2
	v_fma_f32 v154, v34, v2, 0
	v_max_i32_e32 v2, 0, v3
	v_fmac_f32_e32 v154, v35, v2
	v_max_i32_e32 v2, 0, v4
	v_fmac_f32_e32 v154, v36, v2
	v_max_i32_e32 v2, 0, v5
	v_fmac_f32_e32 v154, v37, v2
	v_max_i32_e32 v2, 0, v6
	v_fmac_f32_e32 v154, v38, v2
	v_max_i32_e32 v2, 0, v7
	v_fmac_f32_e32 v154, v39, v2
	v_max_i32_e32 v2, 0, v8
	v_fmac_f32_e32 v154, v40, v2
	v_max_i32_e32 v2, 0, v9
	v_fmac_f32_e32 v154, v41, v2
	v_max_i32_e32 v2, 0, v10
	v_fmac_f32_e32 v154, v42, v2
	v_max_i32_e32 v2, 0, v11
	v_fmac_f32_e32 v154, v43, v2
	v_max_i32_e32 v2, 0, v12
	v_fmac_f32_e32 v154, v44, v2
	v_max_i32_e32 v2, 0, v13
	v_fmac_f32_e32 v154, v45, v2
	v_max_i32_e32 v2, 0, v14
	v_fmac_f32_e32 v154, v46, v2
	v_max_i32_e32 v2, 0, v15
	v_fmac_f32_e32 v154, v47, v2
	v_max_i32_e32 v2, 0, v16
	v_fmac_f32_e32 v154, v48, v2
	v_max_i32_e32 v2, 0, v17
	v_fmac_f32_e32 v154, v49, v2
	s_waitcnt lgkmcnt(4)
	v_mfma_f32_32x32x16_bf16 v[2:17], v[26:29], v[110:113], 0
	v_mfma_f32_32x32x16_bf16 v[2:17], v[18:21], v[106:109], v[2:17]
	v_mfma_f32_32x32x16_bf16 v[2:17], v[22:25], v[102:105], v[2:17]
	v_mfma_f32_32x32x16_bf16 v[2:17], v[30:33], v[98:101], v[2:17]
	v_add_u32_e32 v153, s29, v138
	v_mov_b32_e32 v155, v154
	v_cmp_ge_i32_e32 vcc, s19, v153
	s_nop 0
	v_permlane32_swap_b32_e32 v154, v155
	s_and_b64 s[36:37], s[84:85], vcc
	s_and_saveexec_b64 s[14:15], s[36:37]
	s_cbranch_execz .LBB0_349
	v_add_f32_e32 v154, v154, v155
	v_max_f32_e32 v0, v0, v0
	v_max_f32_e32 v131, v131, v131
	v_max_f32_e32 v0, v0, v154
	v_min_f32_e32 v131, v131, v154
	ds_write_b32 v133, v154
.LBB0_349:
	s_or_b64 exec, exec, s[14:15]
	v_max_i32_e32 v184, 0, v184
	v_fma_f32 v154, v34, v184, 0
	v_max_i32_e32 v184, 0, v185
	v_fmac_f32_e32 v154, v35, v184
	v_max_i32_e32 v184, 0, v186
	v_fmac_f32_e32 v154, v36, v184
	v_max_i32_e32 v184, 0, v187
	v_fmac_f32_e32 v154, v37, v184
	v_max_i32_e32 v184, 0, v188
	v_fmac_f32_e32 v154, v38, v184
	v_max_i32_e32 v184, 0, v189
	v_fmac_f32_e32 v154, v39, v184
	v_max_i32_e32 v184, 0, v190
	v_fmac_f32_e32 v154, v40, v184
	v_max_i32_e32 v184, 0, v191
	v_fmac_f32_e32 v154, v41, v184
	v_max_i32_e32 v184, 0, v192
	v_fmac_f32_e32 v154, v42, v184
	v_max_i32_e32 v184, 0, v193
	v_fmac_f32_e32 v154, v43, v184
	v_max_i32_e32 v184, 0, v194
	v_fmac_f32_e32 v154, v44, v184
	v_max_i32_e32 v184, 0, v195
	v_fmac_f32_e32 v154, v45, v184
	v_max_i32_e32 v184, 0, v196
	v_fmac_f32_e32 v154, v46, v184
	v_max_i32_e32 v184, 0, v197
	v_fmac_f32_e32 v154, v47, v184
	v_max_i32_e32 v184, 0, v198
	v_fmac_f32_e32 v154, v48, v184
	v_max_i32_e32 v184, 0, v199
	v_fmac_f32_e32 v154, v49, v184
	s_waitcnt lgkmcnt(0)
	v_mfma_f32_32x32x16_bf16 v[184:199], v[26:29], v[94:97], 0
	v_mfma_f32_32x32x16_bf16 v[184:199], v[18:21], v[90:93], v[184:199]
	v_mfma_f32_32x32x16_bf16 v[184:199], v[22:25], v[86:89], v[184:199]
	v_mfma_f32_32x32x16_bf16 v[184:199], v[30:33], v[82:85], v[184:199]
	v_add_u32_e32 v99, 64, v153
	v_mov_b32_e32 v98, v154
	v_cmp_ge_i32_e32 vcc, s19, v99
	s_nop 0
	v_permlane32_swap_b32_e32 v154, v98
	s_and_b64 s[36:37], s[84:85], vcc
	s_and_saveexec_b64 s[14:15], s[36:37]
	s_cbranch_execz .LBB0_351
	v_add_f32_e32 v98, v154, v98
	v_max_f32_e32 v0, v0, v0
	v_max_f32_e32 v99, v131, v131
	v_max_f32_e32 v0, v0, v98
	v_min_f32_e32 v131, v99, v98
	ds_write_b32 v133, v98 offset:256
.LBB0_351:
	s_or_b64 exec, exec, s[14:15]
	v_max_i32_e32 v2, 0, v2
	v_fma_f32 v98, v34, v2, 0
	v_max_i32_e32 v2, 0, v3
	v_fmac_f32_e32 v98, v35, v2
	v_max_i32_e32 v2, 0, v4
	v_fmac_f32_e32 v98, v36, v2
	v_max_i32_e32 v2, 0, v5
	v_fmac_f32_e32 v98, v37, v2
	v_max_i32_e32 v2, 0, v6
	v_fmac_f32_e32 v98, v38, v2
	v_max_i32_e32 v2, 0, v7
	v_fmac_f32_e32 v98, v39, v2
	v_max_i32_e32 v2, 0, v8
	v_fmac_f32_e32 v98, v40, v2
	v_max_i32_e32 v2, 0, v9
	v_fmac_f32_e32 v98, v41, v2
	v_max_i32_e32 v2, 0, v10
	v_fmac_f32_e32 v98, v42, v2
	v_max_i32_e32 v2, 0, v11
	v_fmac_f32_e32 v98, v43, v2
	v_max_i32_e32 v2, 0, v12
	v_fmac_f32_e32 v98, v44, v2
	v_max_i32_e32 v2, 0, v13
	v_fmac_f32_e32 v98, v45, v2
	v_max_i32_e32 v2, 0, v14
	v_fmac_f32_e32 v98, v46, v2
	v_max_i32_e32 v2, 0, v15
	v_fmac_f32_e32 v98, v47, v2
	v_max_i32_e32 v2, 0, v16
	v_fmac_f32_e32 v98, v48, v2
	v_max_i32_e32 v2, 0, v17
	v_fmac_f32_e32 v98, v49, v2
	v_add_u32_e32 v83, 0x80, v153
	v_mov_b32_e32 v82, v98
	v_cmp_ge_i32_e32 vcc, s19, v83
	s_nop 0
	v_permlane32_swap_b32_e32 v98, v82
	s_and_b64 s[36:37], s[84:85], vcc
	s_and_saveexec_b64 s[14:15], s[36:37]
	s_cbranch_execz .LBB0_353
	v_add_f32_e32 v82, v98, v82
	v_max_f32_e32 v0, v0, v0
	v_max_f32_e32 v83, v131, v131
	v_max_f32_e32 v0, v0, v82
	v_min_f32_e32 v131, v83, v82
	ds_write_b32 v133, v82 offset:512
.LBB0_353:
	s_or_b64 exec, exec, s[14:15]
	v_max_i32_e32 v184, 0, v184
	v_fma_f32 v184, v34, v184, 0
	v_max_i32_e32 v185, 0, v185
	v_fmac_f32_e32 v184, v35, v185
	v_max_i32_e32 v185, 0, v186
	v_fmac_f32_e32 v184, v36, v185
	v_max_i32_e32 v185, 0, v187
	v_fmac_f32_e32 v184, v37, v185
	v_max_i32_e32 v185, 0, v188
	v_fmac_f32_e32 v184, v38, v185
	v_max_i32_e32 v185, 0, v189
	v_fmac_f32_e32 v184, v39, v185
	v_max_i32_e32 v185, 0, v190
	v_fmac_f32_e32 v184, v40, v185
	v_max_i32_e32 v185, 0, v191
	v_fmac_f32_e32 v184, v41, v185
	v_max_i32_e32 v185, 0, v192
	v_fmac_f32_e32 v184, v42, v185
	v_max_i32_e32 v185, 0, v193
	v_fmac_f32_e32 v184, v43, v185
	v_max_i32_e32 v185, 0, v194
	v_fmac_f32_e32 v184, v44, v185
	v_max_i32_e32 v185, 0, v195
	v_fmac_f32_e32 v184, v45, v185
	v_max_i32_e32 v185, 0, v196
	v_fmac_f32_e32 v184, v46, v185
	v_max_i32_e32 v185, 0, v197
	v_fmac_f32_e32 v184, v47, v185
	v_max_i32_e32 v185, 0, v198
	v_fmac_f32_e32 v184, v48, v185
	v_max_i32_e32 v185, 0, v199
	v_fmac_f32_e32 v184, v49, v185
	v_add_u32_e32 v186, 0xc0, v153
	v_mov_b32_e32 v185, v184
	v_cmp_ge_i32_e32 vcc, s19, v186
	s_nop 0
	v_permlane32_swap_b32_e32 v184, v185
	s_and_b64 s[36:37], s[84:85], vcc
	s_and_saveexec_b64 s[14:15], s[36:37]
	s_cbranch_execz .LBB0_355
	v_add_f32_e32 v184, v184, v185
	v_max_f32_e32 v0, v0, v0
	v_max_f32_e32 v185, v131, v131
	v_max_f32_e32 v0, v0, v184
	v_min_f32_e32 v131, v185, v184
	ds_write_b32 v133, v184 offset:768

.LBB0_360:
	ds_read_b128 v[2:5], v140 offset:0
	ds_read_b128 v[154:157], v140 offset:32
	ds_read_b128 v[158:161], v140 offset:64
	ds_read_b128 v[162:165], v140 offset:0x60
	ds_read_b128 v[166:169], v140 offset:0x2400
	ds_read_b128 v[170:173], v140 offset:0x2420
	ds_read_b128 v[174:177], v140 offset:0x2440
	ds_read_b128 v[178:181], v140 offset:0x2460
	ds_read_b128 v[110:113], v140 offset:0x4800
	ds_read_b128 v[106:109], v140 offset:0x4820
	ds_read_b128 v[102:105], v140 offset:0x4840
	ds_read_b128 v[98:101], v140 offset:0x4860
	ds_read_b128 v[94:97], v140 offset:0x6c00
	ds_read_b128 v[90:93], v140 offset:0x6c20
	ds_read_b128 v[86:89], v140 offset:0x6c40
	ds_read_b128 v[82:85], v140 offset:0x6c60
	s_waitcnt lgkmcnt(12)
	v_mfma_f32_32x32x16_bf16 v[2:17], v[26:29], v[2:5], 0
	v_mfma_f32_32x32x16_bf16 v[2:17], v[18:21], v[154:157], v[2:17]
	v_mfma_f32_32x32x16_bf16 v[2:17], v[22:25], v[158:161], v[2:17]
	v_mfma_f32_32x32x16_bf16 v[2:17], v[30:33], v[162:165], v[2:17]
	s_waitcnt lgkmcnt(8)
	v_mfma_f32_32x32x16_bf16 v[184:199], v[26:29], v[166:169], 0
	v_mfma_f32_32x32x16_bf16 v[184:199], v[18:21], v[170:173], v[184:199]
	v_mfma_f32_32x32x16_bf16 v[184:199], v[22:25], v[174:177], v[184:199]
	v_mfma_f32_32x32x16_bf16 v[184:199], v[30:33], v[178:181], v[184:199]
	s_nop 6
	v_max_i32_e32 v2, 0, v2
	v_fma_f32 v154, v34, v2, 0
	v_max_i32_e32 v2, 0, v3
	v_fmac_f32_e32 v154, v35, v2
	v_max_i32_e32 v2, 0, v4
	v_fmac_f32_e32 v154, v36, v2
	v_max_i32_e32 v2, 0, v5
	v_fmac_f32_e32 v154, v37, v2
	v_max_i32_e32 v2, 0, v6
	v_fmac_f32_e32 v154, v38, v2
	v_max_i32_e32 v2, 0, v7
	v_fmac_f32_e32 v154, v39, v2
	v_max_i32_e32 v2, 0, v8
	v_fmac_f32_e32 v154, v40, v2
	v_max_i32_e32 v2, 0, v9
	v_fmac_f32_e32 v154, v41, v2
	v_max_i32_e32 v2, 0, v10
	v_fmac_f32_e32 v154, v42, v2
	v_max_i32_e32 v2, 0, v11
	v_fmac_f32_e32 v154, v43, v2
	v_max_i32_e32 v2, 0, v12
	v_fmac_f32_e32 v154, v44, v2
	v_max_i32_e32 v2, 0, v13
	v_fmac_f32_e32 v154, v45, v2
	v_max_i32_e32 v2, 0, v14
	v_fmac_f32_e32 v154, v46, v2
	v_max_i32_e32 v2, 0, v15
	v_fmac_f32_e32 v154, v47, v2
	v_max_i32_e32 v2, 0, v16
	v_fmac_f32_e32 v154, v48, v2
	v_max_i32_e32 v2, 0, v17
	v_fmac_f32_e32 v154, v49, v2
	s_waitcnt lgkmcnt(4)
	v_mfma_f32_32x32x16_bf16 v[2:17], v[26:29], v[110:113], 0
	v_mfma_f32_32x32x16_bf16 v[2:17], v[18:21], v[106:109], v[2:17]
	v_mfma_f32_32x32x16_bf16 v[2:17], v[22:25], v[102:105], v[2:17]
	v_mfma_f32_32x32x16_bf16 v[2:17], v[30:33], v[98:101], v[2:17]
	v_add_u32_e32 v156, 0x100, v153
	v_mov_b32_e32 v155, v154
	v_cmp_ge_i32_e32 vcc, s19, v156
	s_nop 0
	v_permlane32_swap_b32_e32 v154, v155
	s_and_b64 s[36:37], s[84:85], vcc
	s_and_saveexec_b64 s[14:15], s[36:37]
	s_cbranch_execz .LBB0_362
	v_add_f32_e32 v154, v154, v155
	v_max_f32_e32 v0, v0, v0
	v_max_f32_e32 v131, v131, v131
	v_max_f32_e32 v0, v0, v154
	v_min_f32_e32 v131, v131, v154
	ds_write_b32 v133, v154 offset:1024
.LBB0_362:
	s_or_b64 exec, exec, s[14:15]
	v_max_i32_e32 v184, 0, v184
	v_fma_f32 v154, v34, v184, 0
	v_max_i32_e32 v184, 0, v185
	v_fmac_f32_e32 v154, v35, v184
	v_max_i32_e32 v184, 0, v186
	v_fmac_f32_e32 v154, v36, v184
	v_max_i32_e32 v184, 0, v187
	v_fmac_f32_e32 v154, v37, v184
	v_max_i32_e32 v184, 0, v188
	v_fmac_f32_e32 v154, v38, v184
	v_max_i32_e32 v184, 0, v189
	v_fmac_f32_e32 v154, v39, v184
	v_max_i32_e32 v184, 0, v190
	v_fmac_f32_e32 v154, v40, v184
	v_max_i32_e32 v184, 0, v191
	v_fmac_f32_e32 v154, v41, v184
	v_max_i32_e32 v184, 0, v192
	v_fmac_f32_e32 v154, v42, v184
	v_max_i32_e32 v184, 0, v193
	v_fmac_f32_e32 v154, v43, v184
	v_max_i32_e32 v184, 0, v194
	v_fmac_f32_e32 v154, v44, v184
	v_max_i32_e32 v184, 0, v195
	v_fmac_f32_e32 v154, v45, v184
	v_max_i32_e32 v184, 0, v196
	v_fmac_f32_e32 v154, v46, v184
	v_max_i32_e32 v184, 0, v197
	v_fmac_f32_e32 v154, v47, v184
	v_max_i32_e32 v184, 0, v198
	v_fmac_f32_e32 v154, v48, v184
	v_max_i32_e32 v184, 0, v199
	v_fmac_f32_e32 v154, v49, v184
	s_waitcnt lgkmcnt(0)
	v_mfma_f32_32x32x16_bf16 v[184:199], v[26:29], v[94:97], 0
	v_mfma_f32_32x32x16_bf16 v[184:199], v[18:21], v[90:93], v[184:199]
	v_mfma_f32_32x32x16_bf16 v[184:199], v[22:25], v[86:89], v[184:199]
	v_mfma_f32_32x32x16_bf16 v[184:199], v[30:33], v[82:85], v[184:199]
	v_add_u32_e32 v99, 0x140, v153
	v_mov_b32_e32 v98, v154
	v_cmp_ge_i32_e32 vcc, s19, v99
	s_nop 0
	v_permlane32_swap_b32_e32 v154, v98
	s_and_b64 s[36:37], s[84:85], vcc
	s_and_saveexec_b64 s[14:15], s[36:37]
	s_cbranch_execz .LBB0_364
	v_add_f32_e32 v98, v154, v98
	v_max_f32_e32 v0, v0, v0
	v_max_f32_e32 v99, v131, v131
	v_max_f32_e32 v0, v0, v98
	v_min_f32_e32 v131, v99, v98
	ds_write_b32 v133, v98 offset:1280
.LBB0_364:
	s_or_b64 exec, exec, s[14:15]
	v_max_i32_e32 v2, 0, v2
	v_fma_f32 v98, v34, v2, 0
	v_max_i32_e32 v2, 0, v3
	v_fmac_f32_e32 v98, v35, v2
	v_max_i32_e32 v2, 0, v4
	v_fmac_f32_e32 v98, v36, v2
	v_max_i32_e32 v2, 0, v5
	v_fmac_f32_e32 v98, v37, v2
	v_max_i32_e32 v2, 0, v6
	v_fmac_f32_e32 v98, v38, v2
	v_max_i32_e32 v2, 0, v7
	v_fmac_f32_e32 v98, v39, v2
	v_max_i32_e32 v2, 0, v8
	v_fmac_f32_e32 v98, v40, v2
	v_max_i32_e32 v2, 0, v9
	v_fmac_f32_e32 v98, v41, v2
	v_max_i32_e32 v2, 0, v10
	v_fmac_f32_e32 v98, v42, v2
	v_max_i32_e32 v2, 0, v11
	v_fmac_f32_e32 v98, v43, v2
	v_max_i32_e32 v2, 0, v12
	v_fmac_f32_e32 v98, v44, v2
	v_max_i32_e32 v2, 0, v13
	v_fmac_f32_e32 v98, v45, v2
	v_max_i32_e32 v2, 0, v14
	v_fmac_f32_e32 v98, v46, v2
	v_max_i32_e32 v2, 0, v15
	v_fmac_f32_e32 v98, v47, v2
	v_max_i32_e32 v2, 0, v16
	v_fmac_f32_e32 v98, v48, v2
	v_max_i32_e32 v2, 0, v17
	v_fmac_f32_e32 v98, v49, v2
	v_add_u32_e32 v83, 0x180, v153
	v_mov_b32_e32 v82, v98
	v_cmp_ge_i32_e32 vcc, s19, v83
	s_nop 0
	v_permlane32_swap_b32_e32 v98, v82
	s_and_b64 s[36:37], s[84:85], vcc
	s_and_saveexec_b64 s[14:15], s[36:37]
	s_cbranch_execz .LBB0_366
	v_add_f32_e32 v82, v98, v82
	v_max_f32_e32 v0, v0, v0
	v_max_f32_e32 v83, v131, v131
	v_max_f32_e32 v0, v0, v82
	v_min_f32_e32 v131, v83, v82
	ds_write_b32 v133, v82 offset:1536
.LBB0_366:
	s_or_b64 exec, exec, s[14:15]
	v_max_i32_e32 v184, 0, v184
	v_fma_f32 v184, v34, v184, 0
	v_max_i32_e32 v185, 0, v185
	v_fmac_f32_e32 v184, v35, v185
	v_max_i32_e32 v185, 0, v186
	v_fmac_f32_e32 v184, v36, v185
	v_max_i32_e32 v185, 0, v187
	v_fmac_f32_e32 v184, v37, v185
	v_max_i32_e32 v185, 0, v188
	v_fmac_f32_e32 v184, v38, v185
	v_max_i32_e32 v185, 0, v189
	v_fmac_f32_e32 v184, v39, v185
	v_max_i32_e32 v185, 0, v190
	v_fmac_f32_e32 v184, v40, v185
	v_max_i32_e32 v185, 0, v191
	v_fmac_f32_e32 v184, v41, v185
	v_max_i32_e32 v185, 0, v192
	v_fmac_f32_e32 v184, v42, v185
	v_max_i32_e32 v185, 0, v193
	v_fmac_f32_e32 v184, v43, v185
	v_max_i32_e32 v185, 0, v194
	v_fmac_f32_e32 v184, v44, v185
	v_max_i32_e32 v185, 0, v195
	v_fmac_f32_e32 v184, v45, v185
	v_max_i32_e32 v185, 0, v196
	v_fmac_f32_e32 v184, v46, v185
	v_max_i32_e32 v185, 0, v197
	v_fmac_f32_e32 v184, v47, v185
	v_max_i32_e32 v185, 0, v198
	v_fmac_f32_e32 v184, v48, v185
	v_max_i32_e32 v185, 0, v199
	v_fmac_f32_e32 v184, v49, v185
	v_add_u32_e32 v186, 0x1c0, v153
	v_mov_b32_e32 v185, v184
	v_cmp_ge_i32_e32 vcc, s19, v186
	s_nop 0
	v_permlane32_swap_b32_e32 v184, v185
	s_and_b64 s[36:37], s[84:85], vcc
	s_and_saveexec_b64 s[14:15], s[36:37]
	s_cbranch_execz .LBB0_368
	v_add_f32_e32 v184, v184, v185
	v_max_f32_e32 v0, v0, v0
	v_max_f32_e32 v185, v131, v131
	v_max_f32_e32 v0, v0, v184
	v_min_f32_e32 v131, v185, v184
	ds_write_b32 v133, v184 offset:1792

; #define WSL(F) ws_opaque((F).ws)
; #define WAVE(F) int_opaque((F).wave)
; #define VCU(F) int_opaque((F).vcu)
; __device__ __forceinline__ const float* karg(int i) { kseg_t ka = (kseg_t)__builtin_amdgcn_kernarg_segment_ptr(); asm volatile("" : "+s"(ka)); return *(const float* const __attribute__((address_space(4)))*)(ka + 8 * i); }
; __device__ __forceinline__ void attn_phase(Frame& F) {
;     const bf16* PROJ = (const bf16*)(WSL(F) + WS_PROJ); bf16* DIFFO = (bf16*)(WSL(F) + WS_DIFFO); bf16* Y = (bf16*)(WSL(F) + WS_Y);
;     const unsigned* MMASK = (const unsigned*)(WSL(F) + WS_MMASK); const float* tab = karg(3);
;     constexpr int ND = NB * DIFF_H * 2, PER_QB = ND + NB * MOBA_H, NU = 16 * PER_QB;
;     const int vcu_ = VCU(F), wave_ = WAVE(F);
;     for (int r = 0;; ++r) {
;         int i;
;         if (F.G == 256) { if (r >= 4) break; const int id = (int)c_attn_sched[vcu_][r]; if (id == 0xFFFF) break; i = (15 - id / PER_QB) * PER_QB + id % PER_QB; }
;         else { i = r * F.G + ((r & 1) ? F.G - 1 - vcu_ : vcu_); if (i >= NU) break; }
;         const int qb = 15 - i / PER_QB, j = i % PER_QB, P0 = qb * 256;
.LBB0_613:
	s_cmp_le_i32 s52, s20
	v_readlane_b32 s18, v255, 19
	s_cselect_b64 s[14:15], -1, 0
	s_mul_i32 s18, s18, 10
	s_and_b64 s[14:15], s[14:15], s[44:45]
	s_add_i32 s54, s18, 5
	s_cmp_lt_i32 s54, s53
	s_cselect_b64 s[34:35], -1, 0
	s_andn2_b64 vcc, exec, s[14:15]
	v_readlane_b32 s19, v255, 20
	s_cbranch_vccnz .LBB0_853
	s_mov_b64 s[14:15], s[96:97]
	s_add_u32 s48, s14, 0x3c900000
	s_addc_u32 s49, s15, 0
	s_mov_b64 s[14:15], s[96:97]
	s_add_u32 s50, s14, 0x6ec00000
	s_addc_u32 s51, s15, 0
	s_mov_b64 s[40:41], s[96:97]
	s_mov_b64 s[14:15], s[96:97]
	s_add_u32 s52, s14, 0x72700000
	s_addc_u32 s53, s15, 0
	v_readlane_b32 s14, v253, 61
	v_readlane_b32 s15, v253, 62
	s_load_dwordx2 s[42:43], s[14:15], 0x18
	v_readlane_b32 s14, v253, 2
	s_mov_b32 s44, s14
	s_ashr_i32 s45, s44, 31
	s_not_b32 s24, s44
	s_lshl_b64 s[14:15], s[44:45], 3
	s_getpc_b64 s[18:19]
	s_add_u32 s18, s18, c_attn_sched@rel32@lo+4
	s_addc_u32 s19, s19, c_attn_sched@rel32@hi+12
	v_readlane_b32 s20, v253, 3
	s_add_u32 s31, s18, s14
	s_addc_u32 s45, s19, s15
	s_lshl_b32 s14, s20, 1
	s_or_b32 s14, s14, 1
	s_lshl_b32 s60, s14, 2
	s_lshl_b32 s61, s14, 1
	s_lshl_b32 s62, s14, 10
	s_lshl_b32 s14, s20, 8
	s_lshl_b32 s56, s20, 5
	s_add_i32 s64, s14, 0
	s_lshl_b32 s55, s20, 6
	s_lshl_b32 s57, s20, 3
	s_and_b32 s32, s57, 8
	s_lshl_b32 s58, s20, 2
	s_lshl_b32 s59, s20, 11
	s_add_i32 s63, s82, s24
	s_add_i32 s64, s64, 0x24800
	s_add_i32 s65, s56, 0xf00
	s_lshl_b32 s66, s20, 7
	s_mov_b32 s20, 0
	s_branch .LBB0_619

; #define LAS __attribute__((address_space(3)))
; __device__ __forceinline__ void qkt(f32x16& p0, f32x16& p1, const LAS char* Kb, int r32, int hi, const bf16x8* qr) {
;     p0 = f32x16{}; p1 = f32x16{};
;     const LAS char* kb[4];
; #pragma unroll
;     for (int dd = 0; dd < 4; ++dd) kb[dd] = Kb + KSWZ(r32, (dd * 16 + hi * 8) * 2);
; template <bool MOBA, int VW>
; __device__ __forceinline__ void unit(LAS unsigned char* lds, const bf16* Q, const bf16* K, const bf16* V, bf16* O, int ldq, int ldk, int ldv, int ldo, int P0,
;                                      const float* biascol, const unsigned* mmask, int mstride, int wave) {
;     ...
;     __syncthreads();
;     for (int i = tid; i < BT_N; i += NW * 64) { const int d = i - BT_PAD; bt[i] = biascol[bucket(d < 0 ? 0 : d) * 32] * (1.f / SCALE); }
;     asm volatile("s_waitcnt vmcnt(0) lgkmcnt(0)" ::: "memory");
;     FA_ISSUE(0); if (NT > 1) FA_ISSUE(1);
.LBB0_633:
	s_or_b64 exec, exec, s[28:29]
	v_mov_b32_e32 v3, v164
	s_waitcnt vmcnt(0) lgkmcnt(0)
	s_lshl_b32 s14, s14, 7
	v_lshlrev_b32_e32 v6, 3, v3
	v_ashrrev_i32_e32 v8, 4, v3
	v_bfe_u32 v2, v3, 2, 2
	v_and_b32_e32 v11, 24, v6
	v_lshrrev_b32_e32 v6, 1, v3
	v_and_b32_e32 v9, 15, v3
	v_and_or_b32 v12, v6, 8, v2
	v_add_u32_e32 v2, s57, v8
	s_lshl_b32 s18, s14, 1
	v_ashrrev_i32_e32 v10, 5, v3
	v_mul_lo_u32 v2, v2, s68
	v_bitop3_b32 v6, v8, v9, 7 bitop3:0x6c
	v_xor_b32_e32 v6, s32, v6
	s_add_u32 s14, s46, s18
	v_lshl_or_b32 v2, v6, 3, v2
	v_add_u32_e32 v6, s58, v10
	s_addc_u32 s15, s47, 0
	v_lshlrev_b32_e32 v7, 1, v6
	s_add_u32 s26, s14, 0x2e00
	v_and_b32_e32 v7, 0xffff0, v7
	v_and_b32_e32 v6, 4, v6
	s_addc_u32 s27, s15, 0
	v_or3_b32 v6, v6, v7, v12
	s_add_u32 s46, s14, 0x3800
	v_and_b32_e32 v3, 0x60, v3
	v_mul_u32_u24_e32 v6, 0x3000, v6
	s_addc_u32 s47, s15, 0
	v_or3_b32 v6, v6, v3, v11
	v_ashrrev_i32_e32 v3, 31, v2
	s_add_i32 s15, s59, 0
	v_lshl_add_u64 v[2:3], v[2:3], 1, s[26:27]
	s_mov_b32 m0, s15
	v_ashrrev_i32_e32 v7, 31, v6
	global_load_lds_dwordx4 v[2:3], off
	v_lshl_add_u64 v[2:3], v[6:7], 1, s[46:47]
	s_add_i32 m0, s15, 0x4000
	s_add_i32 s14, s62, 0
	global_load_lds_dwordx4 v[2:3], off
	v_add_u32_e32 v2, s60, v8
	v_mul_lo_u32 v3, v2, s68
	v_bitop3_b32 v2, v2, v9, 15 bitop3:0x6c
	v_lshl_or_b32 v2, v2, 3, v3
	v_add_u32_e32 v3, s61, v10
	v_lshlrev_b32_e32 v6, 1, v3
	v_lshlrev_b32_e32 v7, 5, v3
	v_and_b32_e32 v6, 0xffff0, v6
	v_and_b32_e32 v3, 4, v3
	v_or3_b32 v3, v3, v6, v12
	v_and_b32_e32 v7, 0x60, v7
	v_mul_u32_u24_e32 v3, 0x3000, v3
	v_or3_b32 v6, v3, v7, v11
	v_ashrrev_i32_e32 v3, 31, v2
	v_lshl_add_u64 v[2:3], v[2:3], 1, s[26:27]
	s_mov_b32 m0, s14
	v_ashrrev_i32_e32 v7, 31, v6
	global_load_lds_dwordx4 v[2:3], off
	v_lshl_add_u64 v[2:3], v[6:7], 1, s[46:47]
	s_add_i32 m0, s14, 0x4000
	v_ashrrev_i32_e32 v161, 31, v160
	global_load_lds_dwordx4 v[2:3], off
	s_cmpk_gt_i32 s74, 0xff7f
	s_cbranch_scc0 .LBB0_635
	v_mov_b32_e32 v3, v164
	s_add_u32 s28, s26, 0x180000
	v_lshlrev_b32_e32 v6, 3, v3
	v_ashrrev_i32_e32 v8, 4, v3
	v_bfe_u32 v2, v3, 2, 2
	v_and_b32_e32 v11, 24, v6
	v_lshrrev_b32_e32 v6, 1, v3
	v_and_b32_e32 v9, 15, v3
	v_and_or_b32 v12, v6, 8, v2
	v_add_u32_e32 v2, s57, v8
	v_ashrrev_i32_e32 v10, 5, v3
	v_mul_lo_u32 v2, v2, s68
	v_bitop3_b32 v6, v8, v9, 7 bitop3:0x6c
	v_xor_b32_e32 v6, s32, v6
	v_lshl_or_b32 v2, v6, 3, v2
	v_add_u32_e32 v6, s58, v10
	v_lshlrev_b32_e32 v7, 1, v6
	v_and_b32_e32 v7, 0xffff0, v7
	v_and_b32_e32 v6, 4, v6
	v_or3_b32 v6, v6, v7, v12
	s_addc_u32 s29, s27, 0
	v_and_b32_e32 v3, 0x60, v3
	v_mul_u32_u24_e32 v6, 0x3000, v6
	s_add_u32 s36, s46, 0x180000
	v_or3_b32 v6, v6, v3, v11
	v_ashrrev_i32_e32 v3, 31, v2
	s_addc_u32 s37, s47, 0
	v_lshl_add_u64 v[2:3], v[2:3], 1, s[28:29]
	s_add_i32 m0, s15, 0xc000
	v_ashrrev_i32_e32 v7, 31, v6
	s_add_i32 s15, 0, 0x10000
	global_load_lds_dwordx4 v[2:3], off
	v_lshl_add_u64 v[2:3], v[6:7], 1, s[36:37]
	s_add_i32 m0, s15, s59
	s_nop 0
	global_load_lds_dwordx4 v[2:3], off
	v_add_u32_e32 v2, s60, v8
	v_mul_lo_u32 v3, v2, s68
	v_bitop3_b32 v2, v2, v9, 15 bitop3:0x6c
	v_lshl_or_b32 v2, v2, 3, v3
	v_add_u32_e32 v3, s61, v10
	v_lshlrev_b32_e32 v6, 1, v3
	v_lshlrev_b32_e32 v7, 5, v3
	v_and_b32_e32 v6, 0xffff0, v6
	v_and_b32_e32 v3, 4, v3
	v_or3_b32 v3, v3, v6, v12
	v_and_b32_e32 v7, 0x60, v7
	v_mul_u32_u24_e32 v3, 0x3000, v3
	v_or3_b32 v6, v3, v7, v11
	v_ashrrev_i32_e32 v3, 31, v2
	v_lshl_add_u64 v[2:3], v[2:3], 1, s[28:29]
	s_add_i32 m0, s14, 0xc000
	v_ashrrev_i32_e32 v7, 31, v6
	global_load_lds_dwordx4 v[2:3], off
	v_lshl_add_u64 v[2:3], v[6:7], 1, s[36:37]
	s_add_i32 m0, s15, s62
	s_nop 0
	global_load_lds_dwordx4 v[2:3], off
.LBB0_635:
	s_cmpk_lt_i32 s74, 0xff40
	s_cbranch_scc1 .LBB0_682
	s_add_i32 s14, s73, 0x1000
	v_lshlrev_b32_e32 v2, 3, v164
	v_lshlrev_b32_e32 v3, 4, v164
	v_and_b32_e32 v3, 0xc0, v3
	v_lshlrev_b32_e32 v6, 1, v164
	v_and_b32_e32 v7, 0x100, v2
	s_ashr_i32 s19, s14, 6
	s_add_i32 s14, 0, 0x4000
	v_and_b32_e32 v6, 32, v6
	v_and_b32_e32 v2, 24, v2
	v_add3_u32 v3, v7, s14, v3
	s_add_i32 s14, s65, s73
	v_add3_u32 v167, v3, v6, v2
	v_add_u32_e32 v2, s14, v0
	s_lshl_b32 s14, s72, 10
	v_lshlrev_b32_e32 v8, 4, v4
	v_lshlrev_b32_e32 v9, 4, v0
	s_add_i32 s14, s66, s14
	v_mul_f32_e32 v166, 0x413504f3, v5
	v_lshlrev_b32_e32 v5, 8, v0
	v_and_b32_e32 v9, 0xf0, v9
	v_add_u32_e32 v10, 32, v8
	v_add_u32_e32 v11, 64, v8
	v_add_u32_e32 v12, 0x60, v8
	v_lshlrev_b32_e32 v4, 2, v4
	v_lshl_add_u32 v0, v0, 2, s14
	v_mov_b32_e32 v14, v1
	v_mov_b32_e32 v15, v1
	v_sub_u32_e32 v168, v2, v4
	v_sub_u32_e32 v169, v0, v8
	v_xad_u32 v170, v12, v9, v5
	v_xad_u32 v171, v11, v9, v5
	v_xad_u32 v172, v10, v9, v5
	v_xad_u32 v173, v9, v8, v5
	v_mov_b32_e32 v0, v1
	v_mov_b32_e32 v2, v1
	v_mov_b32_e32 v3, v1
	v_mov_b32_e32 v4, v1
	v_mov_b32_e32 v5, v1
	v_mov_b32_e32 v6, v1
	v_mov_b32_e32 v7, v1
	v_mov_b32_e32 v8, v1
	v_mov_b32_e32 v9, v1
	v_mov_b32_e32 v10, v1
	v_mov_b32_e32 v11, v1
	v_mov_b32_e32 v12, v1
	v_mov_b32_e32 v13, v1
	v_mov_b64_e32 v[78:79], v[14:15]
	v_mov_b64_e32 v[62:63], v[14:15]
	v_mov_b64_e32 v[46:47], v[14:15]
	v_mov_b64_e32 v[30:31], v[14:15]
	s_ashr_i32 s36, s74, 8
	s_or_b32 s37, s75, 31
	s_addk_i32 s75, 0xff8f
	s_max_i32 s78, s19, 1
	s_mov_b32 s79, 2
	s_mov_b32 s80, 0
	v_mov_b32_e32 v175, 0
	v_mov_b32_e32 v174, 0xf149f2ca
	s_movk_i32 s81, 0x80
	v_mov_b64_e32 v[76:77], v[12:13]
	v_mov_b64_e32 v[74:75], v[10:11]
	v_mov_b64_e32 v[72:73], v[8:9]
	v_mov_b64_e32 v[70:71], v[6:7]
	v_mov_b64_e32 v[68:69], v[4:5]
	v_mov_b64_e32 v[66:67], v[2:3]
	v_mov_b64_e32 v[64:65], v[0:1]
	v_mov_b64_e32 v[60:61], v[12:13]
	v_mov_b64_e32 v[58:59], v[10:11]
	v_mov_b64_e32 v[56:57], v[8:9]
	v_mov_b64_e32 v[54:55], v[6:7]
	v_mov_b64_e32 v[52:53], v[4:5]
	v_mov_b64_e32 v[50:51], v[2:3]
	v_mov_b64_e32 v[48:49], v[0:1]
	v_mov_b64_e32 v[44:45], v[12:13]
	v_mov_b64_e32 v[42:43], v[10:11]
	v_mov_b64_e32 v[40:41], v[8:9]
	v_mov_b64_e32 v[38:39], v[6:7]
	v_mov_b64_e32 v[36:37], v[4:5]
	v_mov_b64_e32 v[34:35], v[2:3]
	v_mov_b64_e32 v[32:33], v[0:1]
	v_mov_b64_e32 v[28:29], v[12:13]
	v_mov_b64_e32 v[26:27], v[10:11]
	v_mov_b64_e32 v[24:25], v[8:9]
	v_mov_b64_e32 v[22:23], v[6:7]
	v_mov_b64_e32 v[20:21], v[4:5]
	v_mov_b64_e32 v[18:19], v[2:3]
	v_mov_b64_e32 v[16:17], v[0:1]
	s_mov_b32 s28, 0
	s_add_i32 s84, s28, 1
	s_cmp_ge_i32 s84, s19
	s_mov_b64 s[14:15], -1
	s_cbranch_scc0 .LBB0_638

; #define LAS __attribute__((address_space(3)))
; #define SBAR() __builtin_amdgcn_sched_barrier(0)
; __device__ __forceinline__ void qkt(f32x16& p0, f32x16& p1, const LAS char* Kb, int r32, int hi, const bf16x8* qr) {
;     ...
;     for (int d0 = 0; d0 < 8; ++d0) { const LAS char* a = kb[d0 & 3] + (d0 >> 2) * 128;
;         const bf16x8 b0 = *(const LAS bf16x8*)a;
;         const bf16x8 b1 = *(const LAS bf16x8*)(a + 32 * 256);
;         p0 = __builtin_amdgcn_mfma_f32_32x32x16_bf16(b0, qr[d0], p0, 0, 0, 0);
;         p1 = __builtin_amdgcn_mfma_f32_32x32x16_bf16(b1, qr[d0], p1, 0, 0, 0); }
; template <bool MOBA, int VW>
; __device__ __forceinline__ void unit(LAS unsigned char* lds, const bf16* Q, const bf16* K, const bf16* V, bf16* O, int ldq, int ldk, int ldv, int ldo, int P0,
;                                      const float* biascol, const unsigned* mmask, int mstride, int wave) {
;     ...
;     for (int t = 0; t < NT; ++t) {
;         const int kb = t * KVBLK; const LAS unsigned char* slot = lds + OFF_RING + (t % NSLOT) * SLOT;
;         if (t + 1 < NT) { if (VW == 2) asm volatile("s_waitcnt vmcnt(6)" ::: "memory"); else asm volatile("s_waitcnt vmcnt(4)" ::: "memory"); } else asm volatile("s_waitcnt vmcnt(0)" ::: "memory");
;         __builtin_amdgcn_s_barrier();
;         asm volatile("" ::: "memory"); SBAR();
;         if (t + 2 < NT) FA_ISSUE(t + 2);
;         if (kb <= qlo + QBLK - 1) {
;         f32x16 p0, p1; float alpha; bf16x8 pa0, pa1, pa2, pa3;
;         qkt(p0, p1, (const LAS char*)slot, r32, hi, qr);
.LBB0_640:
	s_barrier
	s_add_i32 s14, s28, 2
	s_cmp_ge_i32 s14, s19
	s_cbranch_scc1 .LBB0_642
	v_mov_b32_e32 v0, v164
	s_mul_hi_u32 s14, s79, 0xaaaaaaab
	v_lshlrev_b32_e32 v3, 3, v0
	v_ashrrev_i32_e32 v6, 4, v0
	v_bfe_u32 v2, v0, 2, 2
	v_and_b32_e32 v9, 24, v3
	v_lshrrev_b32_e32 v3, 1, v0
	s_lshr_b32 s14, s14, 1
	v_and_b32_e32 v7, 15, v0
	v_and_or_b32 v10, v3, 8, v2
	v_add_u32_e32 v2, s57, v6
	s_mul_i32 s14, s14, 0x24000
	v_ashrrev_i32_e32 v8, 5, v0
	v_mul_lo_u32 v2, v2, s68
	v_bitop3_b32 v3, v6, v7, 7 bitop3:0x6c
	v_xor_b32_e32 v3, s32, v3
	s_sub_i32 s24, s59, s14
	s_mul_i32 s85, s81, 0x6000
	v_lshl_or_b32 v2, v3, 3, v2
	v_add_u32_e32 v3, s58, v8
	s_mul_hi_u32 s29, s81, 0x6000
	s_add_u32 s14, s26, s85
	v_lshlrev_b32_e32 v4, 1, v3
	s_addc_u32 s15, s27, s29
	v_and_b32_e32 v4, 0xffff0, v4
	v_and_b32_e32 v3, 4, v3
	s_add_u32 s88, s46, s85
	v_or3_b32 v3, v3, v4, v10
	s_addc_u32 s89, s47, s29
	v_and_b32_e32 v0, 0x60, v0
	v_mul_u32_u24_e32 v3, 0x3000, v3
	s_add_i32 s24, s80, s24
	v_or3_b32 v4, v3, v0, v9
	v_ashrrev_i32_e32 v3, 31, v2
	s_add_i32 s24, s24, 0
	v_lshl_add_u64 v[2:3], v[2:3], 1, s[14:15]
	s_add_i32 m0, s24, 0x18000
	v_ashrrev_i32_e32 v5, 31, v4
	global_load_lds_dwordx4 v[2:3], off
	v_lshl_add_u64 v[2:3], v[4:5], 1, s[88:89]
	s_add_i32 m0, s24, 0x1c000
	v_add_u32_e32 v0, s60, v6
	global_load_lds_dwordx4 v[2:3], off
	v_mul_lo_u32 v2, v0, s68
	v_bitop3_b32 v0, v0, v7, 15 bitop3:0x6c
	v_lshl_or_b32 v2, v0, 3, v2
	v_add_u32_e32 v0, s61, v8
	v_lshlrev_b32_e32 v3, 1, v0
	v_lshlrev_b32_e32 v4, 5, v0
	v_and_b32_e32 v3, 0xffff0, v3
	v_and_b32_e32 v0, 4, v0
	v_or3_b32 v0, v0, v3, v10
	v_and_b32_e32 v4, 0x60, v4
	v_mul_u32_u24_e32 v0, 0x3000, v0
	v_or3_b32 v4, v0, v4, v9
	v_ashrrev_i32_e32 v3, 31, v2
	v_lshl_add_u64 v[2:3], v[2:3], 1, s[14:15]
	s_add_i32 m0, s24, 0x18400
	v_ashrrev_i32_e32 v5, 31, v4
	global_load_lds_dwordx4 v[2:3], off
	v_lshl_add_u64 v[2:3], v[4:5], 1, s[88:89]
	s_add_i32 m0, s24, 0x1c400
	s_nop 0
	global_load_lds_dwordx4 v[2:3], off
.LBB0_642:
	s_add_i32 s88, s81, 0xffffff80
	s_cmp_gt_i32 s88, s37
	s_cbranch_scc1 .LBB0_680
	s_mul_hi_u32 s14, s28, 0xaaaaaaab
	s_lshr_b32 s85, s14, 1
	s_mul_i32 s85, s85, 0x24000
	v_subrev_u32_e32 v0, s85, v173
	s_add_i32 s14, s80, 0
	v_add_u32_e32 v0, s14, v0
	v_subrev_u32_e32 v6, s85, v172
	v_add_u32_e32 v6, s14, v6
	v_subrev_u32_e32 v7, s85, v171
	v_add_u32_e32 v7, s14, v7
	v_subrev_u32_e32 v8, s85, v170
	v_add_u32_e32 v8, s14, v8
	ds_read_b128 v[176:179], v0
	ds_read_b128 v[180:183], v0 offset:8192
	ds_read_b128 v[184:187], v6
	ds_read_b128 v[188:191], v6 offset:8192
	ds_read_b128 v[192:195], v7
	ds_read_b128 v[196:199], v7 offset:8192
	ds_read_b128 v[200:203], v8
	ds_read_b128 v[204:207], v8 offset:8192
	s_add_i32 s14, s81, 0xffffffbf
	s_cmp_gt_i32 s14, s75
	s_cselect_b64 s[28:29], -1, 0
	s_cmp_le_i32 s14, s75
	s_waitcnt lgkmcnt(7)
	v_mfma_f32_32x32x16_bf16 v[96:111], v[176:179], v[128:131], 0
	v_xor_b32_e32 v0, 0x80, v0
	ds_read_b128 v[176:179], v0
	s_waitcnt lgkmcnt(7)
	v_mfma_f32_32x32x16_bf16 v[80:95], v[180:183], v[128:131], 0
	ds_read_b128 v[180:183], v0 offset:8192
	s_waitcnt lgkmcnt(7)
	v_mfma_f32_32x32x16_bf16 v[96:111], v[184:187], v[132:135], v[96:111]
	v_xor_b32_e32 v6, 0x80, v6
	ds_read_b128 v[184:187], v6
	s_waitcnt lgkmcnt(7)
	v_mfma_f32_32x32x16_bf16 v[80:95], v[188:191], v[132:135], v[80:95]
	ds_read_b128 v[188:191], v6 offset:8192
	s_waitcnt lgkmcnt(7)
	v_mfma_f32_32x32x16_bf16 v[96:111], v[192:195], v[136:139], v[96:111]
	v_xor_b32_e32 v7, 0x80, v7
	ds_read_b128 v[192:195], v7
	s_waitcnt lgkmcnt(7)
	v_mfma_f32_32x32x16_bf16 v[80:95], v[196:199], v[136:139], v[80:95]
	ds_read_b128 v[196:199], v7 offset:8192
	s_waitcnt lgkmcnt(7)
	v_mfma_f32_32x32x16_bf16 v[96:111], v[200:203], v[140:143], v[96:111]
	v_xor_b32_e32 v8, 0x80, v8
	ds_read_b128 v[200:203], v8
	s_waitcnt lgkmcnt(7)
	v_mfma_f32_32x32x16_bf16 v[80:95], v[204:207], v[140:143], v[80:95]
	ds_read_b128 v[204:207], v8 offset:8192
	s_waitcnt lgkmcnt(7)
	v_mfma_f32_32x32x16_bf16 v[96:111], v[176:179], v[144:147], v[96:111]
	s_waitcnt lgkmcnt(6)
	v_mfma_f32_32x32x16_bf16 v[80:95], v[180:183], v[144:147], v[80:95]
	s_waitcnt lgkmcnt(5)
	v_mfma_f32_32x32x16_bf16 v[96:111], v[184:187], v[148:151], v[96:111]
	s_waitcnt lgkmcnt(4)
	v_mfma_f32_32x32x16_bf16 v[80:95], v[188:191], v[148:151], v[80:95]
	s_waitcnt lgkmcnt(3)
	v_mfma_f32_32x32x16_bf16 v[96:111], v[192:195], v[152:155], v[96:111]
	s_waitcnt lgkmcnt(2)
	v_mfma_f32_32x32x16_bf16 v[80:95], v[196:199], v[152:155], v[80:95]
	s_waitcnt lgkmcnt(1)
	v_mfma_f32_32x32x16_bf16 v[96:111], v[200:203], v[156:159], v[96:111]
	s_waitcnt lgkmcnt(0)
	s_nop 0
	v_mfma_f32_32x32x16_bf16 v[80:95], v[204:207], v[156:159], v[80:95]
	s_cbranch_scc1 .LBB0_677
; #define LAS __attribute__((address_space(3)))
; __device__ __forceinline__ void bias_mask_tile(f32x16& p0, f32x16& p1, int dq, const LAS float* bt) {
;     const float NEG = -__builtin_inff();
;     const LAS float* b = bt + BT_PAD + dq - 59;
; #pragma unroll
;     for (int r = 0; r < 16; ++r) {
;         const int c = (r & 3) + 8 * (r >> 2);
;         const float v0 = b[59 - c], v1 = b[59 - c - 32];
;         p0[r] = (dq - c) >= 0 ? p0[r] + v0 : NEG;
;         p1[r] = (dq - c - 32) >= 0 ? p1[r] + v1 : NEG;
;     }
; }
	v_add_u32_e32 v2, 0x28494, v169
	ds_read2_b32 v[112:113], v2 offset0:59 offset1:58
	ds_read2_b32 v[114:115], v2 offset0:57 offset1:56
	ds_read2_b32 v[116:117], v2 offset0:51 offset1:50
	ds_read2_b32 v[118:119], v2 offset0:49 offset1:48
	ds_read2_b32 v[120:121], v2 offset0:43 offset1:42
	ds_read2_b32 v[122:123], v2 offset0:41 offset1:40
	ds_read2_b32 v[124:125], v2 offset0:35 offset1:34
	ds_read2_b32 v[126:127], v2 offset0:33 offset1:32
	ds_read2_b32 v[208:209], v2 offset0:27 offset1:26
	ds_read2_b32 v[210:211], v2 offset0:25 offset1:24
	ds_read2_b32 v[212:213], v2 offset0:19 offset1:18
	ds_read2_b32 v[214:215], v2 offset0:17 offset1:16
	ds_read2_b32 v[216:217], v2 offset0:11 offset1:10
	ds_read2_b32 v[218:219], v2 offset0:9 offset1:8
	ds_read2_b32 v[220:221], v2 offset0:3 offset1:2
	ds_read2_b32 v[222:223], v2 offset0:1 offset1:0
	s_waitcnt lgkmcnt(0)
	v_add_f32_e32 v112, v96, v112
	v_cmp_lt_i32_e64 s[14:15], -1, v168
	v_add_f32_e32 v113, v97, v113
	v_cmp_lt_i32_e64 vcc, 0, v168
	v_add_f32_e32 v114, v98, v114
	v_cmp_lt_i32_e64 s[90:91], 1, v168
	v_cndmask_b32_e64 v96, v239, v112, s[14:15]
	v_add_f32_e32 v115, v99, v115
	v_cmp_lt_i32_e64 s[98:99], 2, v168
	v_cndmask_b32_e64 v97, v239, v113, vcc
	v_add_f32_e32 v116, v100, v116
	v_cmp_lt_i32_e64 s[14:15], 7, v168
	v_cndmask_b32_e64 v98, v239, v114, s[90:91]
	v_add_f32_e32 v117, v101, v117
	v_cmp_lt_i32_e64 vcc, 8, v168
	v_cndmask_b32_e64 v99, v239, v115, s[98:99]
	v_add_f32_e32 v118, v102, v118
	v_cmp_lt_i32_e64 s[90:91], 9, v168
	v_cndmask_b32_e64 v100, v239, v116, s[14:15]
	v_add_f32_e32 v119, v103, v119
	v_cmp_lt_i32_e64 s[98:99], 10, v168
	v_cndmask_b32_e64 v101, v239, v117, vcc
	v_add_f32_e32 v120, v104, v120
	v_cmp_lt_i32_e64 s[14:15], 15, v168
	v_cndmask_b32_e64 v102, v239, v118, s[90:91]
	v_add_f32_e32 v121, v105, v121
	v_cmp_lt_i32_e64 vcc, 16, v168
	v_cndmask_b32_e64 v103, v239, v119, s[98:99]
	v_add_f32_e32 v122, v106, v122
	v_cmp_lt_i32_e64 s[90:91], 17, v168
	v_cndmask_b32_e64 v104, v239, v120, s[14:15]
	v_add_f32_e32 v123, v107, v123
	v_cmp_lt_i32_e64 s[98:99], 18, v168
	v_cndmask_b32_e64 v105, v239, v121, vcc
	v_add_f32_e32 v124, v108, v124
	v_cmp_lt_i32_e64 s[14:15], 23, v168
	v_cndmask_b32_e64 v106, v239, v122, s[90:91]
	v_add_f32_e32 v125, v109, v125
	v_cmp_lt_i32_e64 vcc, 24, v168
	v_cndmask_b32_e64 v107, v239, v123, s[98:99]
	v_add_f32_e32 v126, v110, v126
	v_cmp_lt_i32_e64 s[90:91], 25, v168
	v_cndmask_b32_e64 v108, v239, v124, s[14:15]
	v_add_f32_e32 v127, v111, v127
	v_cmp_lt_i32_e64 s[98:99], 26, v168
	v_cndmask_b32_e64 v109, v239, v125, vcc
	v_add_f32_e32 v208, v80, v208
	v_cmp_lt_i32_e64 s[14:15], 31, v168
	v_cndmask_b32_e64 v110, v239, v126, s[90:91]
	v_add_f32_e32 v209, v81, v209
	v_cmp_lt_i32_e64 vcc, 32, v168
	v_cndmask_b32_e64 v111, v239, v127, s[98:99]
	v_add_f32_e32 v210, v82, v210
	v_cmp_lt_i32_e64 s[90:91], 33, v168
	v_cndmask_b32_e64 v80, v239, v208, s[14:15]
	v_add_f32_e32 v211, v83, v211
	v_cmp_lt_i32_e64 s[98:99], 34, v168
	v_cndmask_b32_e64 v81, v239, v209, vcc
	v_add_f32_e32 v212, v84, v212
	v_cmp_lt_i32_e64 s[14:15], 39, v168
	v_cndmask_b32_e64 v82, v239, v210, s[90:91]
	v_add_f32_e32 v213, v85, v213
	v_cmp_lt_i32_e64 vcc, 40, v168
	v_cndmask_b32_e64 v83, v239, v211, s[98:99]
	v_add_f32_e32 v214, v86, v214
	v_cmp_lt_i32_e64 s[90:91], 41, v168
	v_cndmask_b32_e64 v84, v239, v212, s[14:15]
	v_add_f32_e32 v215, v87, v215
	v_cmp_lt_i32_e64 s[98:99], 42, v168
	v_cndmask_b32_e64 v85, v239, v213, vcc
	v_add_f32_e32 v216, v88, v216
	v_cmp_lt_i32_e64 s[14:15], 47, v168
	v_cndmask_b32_e64 v86, v239, v214, s[90:91]
	v_add_f32_e32 v217, v89, v217
	v_cmp_lt_i32_e64 vcc, 48, v168
	v_cndmask_b32_e64 v87, v239, v215, s[98:99]
	v_add_f32_e32 v218, v90, v218
	v_cmp_lt_i32_e64 s[90:91], 49, v168
	v_cndmask_b32_e64 v88, v239, v216, s[14:15]
	v_add_f32_e32 v219, v91, v219
	v_cmp_lt_i32_e64 s[98:99], 50, v168
	v_cndmask_b32_e64 v89, v239, v217, vcc
	v_add_f32_e32 v220, v92, v220
	v_cmp_lt_i32_e64 s[14:15], 55, v168
	v_cndmask_b32_e64 v90, v239, v218, s[90:91]
	v_add_f32_e32 v221, v93, v221
	v_cmp_lt_i32_e64 vcc, 56, v168
	v_cndmask_b32_e64 v91, v239, v219, s[98:99]
	v_add_f32_e32 v222, v94, v222
	v_cmp_lt_i32_e64 s[90:91], 57, v168
	v_cndmask_b32_e64 v92, v239, v220, s[14:15]
	v_add_f32_e32 v223, v95, v223
	v_cmp_lt_i32_e64 s[98:99], 58, v168
	v_cndmask_b32_e64 v93, v239, v221, vcc
	s_nop 0
	v_cndmask_b32_e64 v94, v239, v222, s[90:91]
	v_cndmask_b32_e64 v95, v239, v223, s[98:99]

; template <bool MOBA, int VW>
; __device__ __forceinline__ void unit(LAS unsigned char* lds, const bf16* Q, const bf16* K, const bf16* V, bf16* O, int ldq, int ldk, int ldv, int ldo, int P0,
;                                      const float* biascol, const unsigned* mmask, int mstride, int wave) {
;     ...
;     __syncthreads();
;     for (int i = tid; i < BT_N; i += NW * 64) { const int d = i - BT_PAD; bt[i] = biascol[bucket(d < 0 ? 0 : d) * 32] * (1.f / SCALE); }
;     asm volatile("s_waitcnt vmcnt(0) lgkmcnt(0)" ::: "memory");
;     FA_ISSUE(0); if (NT > 1) FA_ISSUE(1);
.LBB0_690:
	s_or_b64 exec, exec, s[36:37]
	v_mov_b32_e32 v3, v251
	s_waitcnt vmcnt(0) lgkmcnt(0)
	s_add_u32 s14, s46, s14
	v_lshlrev_b32_e32 v6, 3, v3
	v_ashrrev_i32_e32 v8, 4, v3
	v_bfe_u32 v2, v3, 2, 2
	v_and_b32_e32 v11, 24, v6
	v_lshrrev_b32_e32 v6, 1, v3
	v_and_b32_e32 v9, 15, v3
	v_and_or_b32 v12, v6, 8, v2
	v_add_u32_e32 v2, s57, v8
	v_ashrrev_i32_e32 v10, 5, v3
	v_mul_lo_u32 v2, v2, s68
	v_bitop3_b32 v6, v8, v9, 7 bitop3:0x6c
	v_xor_b32_e32 v6, s32, v6
	v_lshl_or_b32 v2, v6, 3, v2
	v_add_u32_e32 v6, s58, v10
	v_lshlrev_b32_e32 v7, 1, v6
	v_and_b32_e32 v7, 0xffff0, v7
	v_and_b32_e32 v6, 4, v6
	v_or3_b32 v6, v6, v7, v12
	s_addc_u32 s15, s47, s15
	v_and_b32_e32 v3, 0x60, v3
	v_mul_u32_u24_e32 v6, 0x3000, v6
	s_add_u32 s46, s14, 0x1800
	v_or3_b32 v6, v6, v3, v11
	v_ashrrev_i32_e32 v3, 31, v2
	s_addc_u32 s47, s15, 0
	v_lshl_add_u64 v[2:3], v[2:3], 1, s[26:27]
	s_mov_b64 s[28:29], 0xc00
	s_add_i32 s14, s59, 0
	v_lshl_add_u64 v[2:3], v[2:3], 0, s[28:29]
	s_mov_b32 m0, s14
	v_ashrrev_i32_e32 v7, 31, v6
	global_load_lds_dwordx4 v[2:3], off
	v_lshl_add_u64 v[2:3], v[6:7], 1, s[46:47]
	s_add_i32 m0, s14, 0x4000
	s_mov_b64 s[18:19], 0x100
	global_load_lds_dwordx4 v[2:3], off
	v_lshl_add_u64 v[2:3], v[2:3], 0, s[18:19]
	s_add_i32 m0, s14, 0x8000
	s_add_i32 s15, s62, 0
	global_load_lds_dwordx4 v[2:3], off
	v_add_u32_e32 v2, s60, v8
	v_mul_lo_u32 v3, v2, s68
	v_bitop3_b32 v2, v2, v9, 15 bitop3:0x6c
	v_lshl_or_b32 v2, v2, 3, v3
	v_add_u32_e32 v3, s61, v10
	v_lshlrev_b32_e32 v6, 1, v3
	v_lshlrev_b32_e32 v7, 5, v3
	v_and_b32_e32 v6, 0xffff0, v6
	v_and_b32_e32 v3, 4, v3
	v_or3_b32 v3, v3, v6, v12
	v_and_b32_e32 v7, 0x60, v7
	v_mul_u32_u24_e32 v3, 0x3000, v3
	v_or3_b32 v6, v3, v7, v11
	v_ashrrev_i32_e32 v3, 31, v2
	v_lshl_add_u64 v[2:3], v[2:3], 1, s[26:27]
	v_lshl_add_u64 v[2:3], v[2:3], 0, s[28:29]
	s_mov_b32 m0, s15
	v_ashrrev_i32_e32 v7, 31, v6
	global_load_lds_dwordx4 v[2:3], off
	v_lshl_add_u64 v[2:3], v[6:7], 1, s[46:47]
	s_add_i32 m0, s15, 0x4000
	s_nop 0
	global_load_lds_dwordx4 v[2:3], off
	v_lshl_add_u64 v[2:3], v[2:3], 0, s[18:19]
	s_add_i32 m0, s15, 0x8000
	s_cmpk_gt_i32 s74, 0xff7f
	global_load_lds_dwordx4 v[2:3], off
	s_cbranch_scc0 .LBB0_692
	v_mov_b32_e32 v3, v251
	s_add_u32 s18, s26, 0x180c00
	v_lshlrev_b32_e32 v6, 3, v3
	v_ashrrev_i32_e32 v8, 4, v3
	v_bfe_u32 v2, v3, 2, 2
	v_and_b32_e32 v11, 24, v6
	v_lshrrev_b32_e32 v6, 1, v3
	v_and_b32_e32 v9, 15, v3
	v_and_or_b32 v12, v6, 8, v2
	v_add_u32_e32 v2, s57, v8
	v_ashrrev_i32_e32 v10, 5, v3
	v_mul_lo_u32 v2, v2, s68
	v_bitop3_b32 v6, v8, v9, 7 bitop3:0x6c
	v_xor_b32_e32 v6, s32, v6
	v_lshl_or_b32 v2, v6, 3, v2
	v_add_u32_e32 v6, s58, v10
	v_lshlrev_b32_e32 v7, 1, v6
	v_and_b32_e32 v7, 0xffff0, v7
	v_and_b32_e32 v6, 4, v6
	s_addc_u32 s19, s27, 0
	v_or3_b32 v6, v6, v7, v12
	s_add_u32 s28, s46, 0x180000
	v_and_b32_e32 v3, 0x60, v3
	v_mul_u32_u24_e32 v6, 0x3000, v6
	s_addc_u32 s29, s47, 0
	v_or3_b32 v6, v6, v3, v11
	v_ashrrev_i32_e32 v3, 31, v2
	s_add_i32 m0, s14, 0xc000
	s_add_i32 s14, 0, 0x10000
	v_lshl_add_u64 v[2:3], v[2:3], 1, s[18:19]
	v_ashrrev_i32_e32 v7, 31, v6
	s_add_i32 s24, s14, s59
	global_load_lds_dwordx4 v[2:3], off
	v_lshl_add_u64 v[2:3], v[6:7], 1, s[28:29]
	s_mov_b32 m0, s24
	s_mov_b64 s[36:37], 0x100
	global_load_lds_dwordx4 v[2:3], off
	v_lshl_add_u64 v[2:3], v[2:3], 0, s[36:37]
	s_add_i32 m0, s24, 0x4000
	s_add_i32 s14, s14, s62
	global_load_lds_dwordx4 v[2:3], off
	v_add_u32_e32 v2, s60, v8
	v_mul_lo_u32 v3, v2, s68
	v_bitop3_b32 v2, v2, v9, 15 bitop3:0x6c
	v_lshl_or_b32 v2, v2, 3, v3
	v_add_u32_e32 v3, s61, v10
	v_lshlrev_b32_e32 v6, 1, v3
	v_lshlrev_b32_e32 v7, 5, v3
	v_and_b32_e32 v6, 0xffff0, v6
	v_and_b32_e32 v3, 4, v3
	v_or3_b32 v3, v3, v6, v12
	v_and_b32_e32 v7, 0x60, v7
	v_mul_u32_u24_e32 v3, 0x3000, v3
	v_or3_b32 v6, v3, v7, v11
	v_ashrrev_i32_e32 v3, 31, v2
	v_lshl_add_u64 v[2:3], v[2:3], 1, s[18:19]
	s_add_i32 m0, s15, 0xc000
	v_ashrrev_i32_e32 v7, 31, v6
	global_load_lds_dwordx4 v[2:3], off
	v_lshl_add_u64 v[2:3], v[6:7], 1, s[28:29]
	s_mov_b32 m0, s14
	s_nop 0
	global_load_lds_dwordx4 v[2:3], off
	v_lshl_add_u64 v[2:3], v[2:3], 0, s[36:37]
	s_add_i32 m0, s14, 0x4000
	s_nop 0
	global_load_lds_dwordx4 v[2:3], off
; #define LAS __attribute__((address_space(3)))
; __device__ __forceinline__ int v_rd_base(int lane) { return ((lane & 3) << 3) | (((lane >> 2) & 3) << 6) | (((lane >> 4) & 1) << 5) | (((lane >> 5) & 1) << 8); }
; __device__ __forceinline__ void qkt(f32x16& p0, f32x16& p1, const LAS char* Kb, int r32, int hi, const bf16x8* qr) {
;     p0 = f32x16{}; p1 = f32x16{};
;     const LAS char* kb[4];
; #pragma unroll
;     for (int dd = 0; dd < 4; ++dd) kb[dd] = Kb + KSWZ(r32, (dd * 16 + hi * 8) * 2);
; template <bool MOBA, int VW>
; __device__ __forceinline__ void unit(LAS unsigned char* lds, const bf16* Q, const bf16* K, const bf16* V, bf16* O, int ldq, int ldk, int ldv, int ldo, int P0,
;                                      const float* biascol, const unsigned* mmask, int mstride, int wave) {
;     ...
;     float m_reg = -1e30f, l_reg = 0.f; f32x16 o[4 * VW] = {};
;     const int vrb = v_rd_base(lane);
.LBB0_692:
	s_cmpk_lt_i32 s74, 0xff40
	s_cbranch_scc1 .LBB0_615
	s_add_i32 s14, s73, 0x1000
	v_mul_f32_e32 v245, 0x413504f3, v5
	v_lshlrev_b32_e32 v5, 4, v4
	s_ashr_i32 s18, s14, 6
	v_lshlrev_b32_e32 v8, 4, v0
	s_movk_i32 s14, 0xf0
	v_add_u32_e32 v9, 32, v5
	v_lshlrev_b32_e32 v2, 3, v251
	v_lshlrev_b32_e32 v3, 4, v251
	v_bitop3_b32 v225, v9, v8, s14 bitop3:0x78
	v_add_u32_e32 v9, 64, v5
	v_and_b32_e32 v3, 0xc0, v3
	v_lshlrev_b32_e32 v6, 1, v251
	v_and_b32_e32 v7, 0x100, v2
	v_bitop3_b32 v226, v9, v8, s14 bitop3:0x78
	v_add_u32_e32 v9, 0x60, v5
	v_and_b32_e32 v6, 32, v6
	v_and_b32_e32 v2, 24, v2
	v_bitop3_b32 v224, v8, v5, s14 bitop3:0x6c
	v_bitop3_b32 v227, v9, v8, s14 bitop3:0x78
	v_add3_u32 v3, v7, 0, v3
	s_add_i32 s14, s65, s73
	v_add3_u32 v250, v3, v6, v2
	v_add_u32_e32 v2, s14, v0
	s_lshl_b32 s14, s72, 10
	s_add_i32 s14, s66, s14
	v_lshlrev_b32_e32 v4, 2, v4
	v_lshl_add_u32 v229, v0, 8, 0
	v_lshl_add_u32 v0, v0, 2, s14
	v_mov_b32_e32 v14, v1
	v_mov_b32_e32 v15, v1
	v_sub_u32_e32 v228, v2, v4
	v_sub_u32_e32 v230, v0, v5
	v_mov_b32_e32 v0, v1
	v_mov_b32_e32 v2, v1
	v_mov_b32_e32 v3, v1
	v_mov_b32_e32 v4, v1
	v_mov_b32_e32 v5, v1
	v_mov_b32_e32 v6, v1
	v_mov_b32_e32 v7, v1
	v_mov_b32_e32 v8, v1
	v_mov_b32_e32 v9, v1
	v_mov_b32_e32 v10, v1
	v_mov_b32_e32 v11, v1
	v_mov_b32_e32 v12, v1
	v_mov_b32_e32 v13, v1
	v_mov_b64_e32 v[142:143], v[14:15]
	v_mov_b64_e32 v[126:127], v[14:15]
	v_mov_b64_e32 v[110:111], v[14:15]
	v_mov_b64_e32 v[94:95], v[14:15]
	v_mov_b64_e32 v[78:79], v[14:15]
	v_mov_b64_e32 v[62:63], v[14:15]
	v_mov_b64_e32 v[46:47], v[14:15]
	v_mov_b64_e32 v[30:31], v[14:15]
	s_or_b32 s19, s79, 31
	s_add_i32 s36, s79, 0xffffff8f
	s_max_i32 s37, s18, 1
	s_mov_b32 s38, 2
	s_mov_b32 s39, 0
	v_mov_b32_e32 v236, 0
	v_mov_b32_e32 v231, 0xf149f2ca
	s_movk_i32 s72, 0x80
	v_mov_b64_e32 v[140:141], v[12:13]
	v_mov_b64_e32 v[138:139], v[10:11]
	v_mov_b64_e32 v[136:137], v[8:9]
	v_mov_b64_e32 v[134:135], v[6:7]
	v_mov_b64_e32 v[132:133], v[4:5]
	v_mov_b64_e32 v[130:131], v[2:3]
	v_mov_b64_e32 v[128:129], v[0:1]
	v_mov_b64_e32 v[124:125], v[12:13]
	v_mov_b64_e32 v[122:123], v[10:11]
	v_mov_b64_e32 v[120:121], v[8:9]
	v_mov_b64_e32 v[118:119], v[6:7]
	v_mov_b64_e32 v[116:117], v[4:5]
	v_mov_b64_e32 v[114:115], v[2:3]
	v_mov_b64_e32 v[112:113], v[0:1]
	v_mov_b64_e32 v[108:109], v[12:13]
	v_mov_b64_e32 v[106:107], v[10:11]
	v_mov_b64_e32 v[104:105], v[8:9]
	v_mov_b64_e32 v[102:103], v[6:7]
	v_mov_b64_e32 v[100:101], v[4:5]
	v_mov_b64_e32 v[98:99], v[2:3]
	v_mov_b64_e32 v[96:97], v[0:1]
	v_mov_b64_e32 v[92:93], v[12:13]
	v_mov_b64_e32 v[90:91], v[10:11]
	v_mov_b64_e32 v[88:89], v[8:9]
	v_mov_b64_e32 v[86:87], v[6:7]
	v_mov_b64_e32 v[84:85], v[4:5]
	v_mov_b64_e32 v[82:83], v[2:3]
	v_mov_b64_e32 v[80:81], v[0:1]
	v_mov_b64_e32 v[76:77], v[12:13]
	v_mov_b64_e32 v[74:75], v[10:11]
	v_mov_b64_e32 v[72:73], v[8:9]
	v_mov_b64_e32 v[70:71], v[6:7]
	v_mov_b64_e32 v[68:69], v[4:5]
	v_mov_b64_e32 v[66:67], v[2:3]
	v_mov_b64_e32 v[64:65], v[0:1]
	v_mov_b64_e32 v[60:61], v[12:13]
	v_mov_b64_e32 v[58:59], v[10:11]
	v_mov_b64_e32 v[56:57], v[8:9]
	v_mov_b64_e32 v[54:55], v[6:7]
	v_mov_b64_e32 v[52:53], v[4:5]
	v_mov_b64_e32 v[50:51], v[2:3]
	v_mov_b64_e32 v[48:49], v[0:1]
	v_mov_b64_e32 v[44:45], v[12:13]
	v_mov_b64_e32 v[42:43], v[10:11]
	v_mov_b64_e32 v[40:41], v[8:9]
	v_mov_b64_e32 v[38:39], v[6:7]
	v_mov_b64_e32 v[36:37], v[4:5]
	v_mov_b64_e32 v[34:35], v[2:3]
	v_mov_b64_e32 v[32:33], v[0:1]
	v_mov_b64_e32 v[28:29], v[12:13]
	v_mov_b64_e32 v[26:27], v[10:11]
	v_mov_b64_e32 v[24:25], v[8:9]
	v_mov_b64_e32 v[22:23], v[6:7]
	v_mov_b64_e32 v[20:21], v[4:5]
	v_mov_b64_e32 v[18:19], v[2:3]
	v_mov_b64_e32 v[16:17], v[0:1]
	s_mov_b32 s28, 0
	s_add_i32 s73, s28, 1
	s_cmp_ge_i32 s73, s18
	s_mov_b64 s[14:15], -1
	s_cbranch_scc0 .LBB0_695

; #define LAS __attribute__((address_space(3)))
; #define SBAR() __builtin_amdgcn_sched_barrier(0)
; __device__ __forceinline__ void qkt(f32x16& p0, f32x16& p1, const LAS char* Kb, int r32, int hi, const bf16x8* qr) {
;     ...
;     for (int d0 = 0; d0 < 8; ++d0) { const LAS char* a = kb[d0 & 3] + (d0 >> 2) * 128;
;         const bf16x8 b0 = *(const LAS bf16x8*)a;
;         const bf16x8 b1 = *(const LAS bf16x8*)(a + 32 * 256);
;         p0 = __builtin_amdgcn_mfma_f32_32x32x16_bf16(b0, qr[d0], p0, 0, 0, 0);
;         p1 = __builtin_amdgcn_mfma_f32_32x32x16_bf16(b1, qr[d0], p1, 0, 0, 0); }
; template <bool MOBA, int VW>
; __device__ __forceinline__ void unit(LAS unsigned char* lds, const bf16* Q, const bf16* K, const bf16* V, bf16* O, int ldq, int ldk, int ldv, int ldo, int P0,
;                                      const float* biascol, const unsigned* mmask, int mstride, int wave) {
;     ...
;     for (int t = 0; t < NT; ++t) {
;         const int kb = t * KVBLK; const LAS unsigned char* slot = lds + OFF_RING + (t % NSLOT) * SLOT;
;         if (t + 1 < NT) { if (VW == 2) asm volatile("s_waitcnt vmcnt(6)" ::: "memory"); else asm volatile("s_waitcnt vmcnt(4)" ::: "memory"); } else asm volatile("s_waitcnt vmcnt(0)" ::: "memory");
;         __builtin_amdgcn_s_barrier();
;         asm volatile("" ::: "memory"); SBAR();
;         if (t + 2 < NT) FA_ISSUE(t + 2);
;         if (kb <= qlo + QBLK - 1) {
;         f32x16 p0, p1; float alpha; bf16x8 pa0, pa1, pa2, pa3;
;         qkt(p0, p1, (const LAS char*)slot, r32, hi, qr);
.LBB0_697:
	s_barrier
	s_add_i32 s14, s28, 2
	s_cmp_ge_i32 s14, s18
	s_cbranch_scc1 .LBB0_699
	v_mov_b32_e32 v0, v251
	s_mul_hi_u32 s14, s38, 0xaaaaaaab
	v_lshlrev_b32_e32 v3, 3, v0
	v_ashrrev_i32_e32 v6, 4, v0
	v_bfe_u32 v2, v0, 2, 2
	v_and_b32_e32 v9, 24, v3
	v_lshrrev_b32_e32 v3, 1, v0
	v_and_b32_e32 v7, 15, v0
	v_and_or_b32 v10, v3, 8, v2
	v_add_u32_e32 v2, s57, v6
	s_lshr_b32 s14, s14, 1
	v_ashrrev_i32_e32 v8, 5, v0
	v_mul_lo_u32 v2, v2, s68
	v_bitop3_b32 v3, v6, v7, 7 bitop3:0x6c
	v_xor_b32_e32 v3, s32, v3
	s_mul_i32 s14, s14, 0x24000
	v_lshl_or_b32 v2, v3, 3, v2
	v_add_u32_e32 v3, s58, v8
	s_sub_i32 s24, s59, s14
	s_mul_i32 s74, s72, 0x6000
	v_lshlrev_b32_e32 v4, 1, v3
	s_mul_hi_u32 s29, s72, 0x6000
	s_add_u32 s14, s26, s74
	v_and_b32_e32 v4, 0xffff0, v4
	v_and_b32_e32 v3, 4, v3
	s_addc_u32 s15, s27, s29
	v_or3_b32 v3, v3, v4, v10
	s_add_u32 s80, s46, s74
	v_and_b32_e32 v0, 0x60, v0
	v_mul_u32_u24_e32 v3, 0x3000, v3
	s_addc_u32 s81, s47, s29
	v_or3_b32 v4, v3, v0, v9
	v_ashrrev_i32_e32 v3, 31, v2
	s_add_i32 s24, s39, s24
	v_lshl_add_u64 v[2:3], v[2:3], 1, s[14:15]
	s_mov_b64 s[88:89], 0xc00
	s_add_i32 s24, s24, 0
	v_lshl_add_u64 v[2:3], v[2:3], 0, s[88:89]
	s_add_i32 m0, s24, 0x18000
	v_ashrrev_i32_e32 v5, 31, v4
	global_load_lds_dwordx4 v[2:3], off
	v_lshl_add_u64 v[2:3], v[4:5], 1, s[80:81]
	s_add_i32 m0, s24, 0x1c000
	s_mov_b64 s[84:85], 0x100
	global_load_lds_dwordx4 v[2:3], off
	v_lshl_add_u64 v[2:3], v[2:3], 0, s[84:85]
	s_add_i32 m0, s24, 0x20000
	v_add_u32_e32 v0, s60, v6
	global_load_lds_dwordx4 v[2:3], off
	v_mul_lo_u32 v2, v0, s68
	v_bitop3_b32 v0, v0, v7, 15 bitop3:0x6c
	v_lshl_or_b32 v2, v0, 3, v2
	v_add_u32_e32 v0, s61, v8
	v_lshlrev_b32_e32 v3, 1, v0
	v_lshlrev_b32_e32 v4, 5, v0
	v_and_b32_e32 v3, 0xffff0, v3
	v_and_b32_e32 v0, 4, v0
	v_or3_b32 v0, v0, v3, v10
	v_and_b32_e32 v4, 0x60, v4
	v_mul_u32_u24_e32 v0, 0x3000, v0
	v_ashrrev_i32_e32 v3, 31, v2
	v_or3_b32 v4, v0, v4, v9
	v_lshl_add_u64 v[2:3], v[2:3], 1, s[14:15]
	v_lshl_add_u64 v[2:3], v[2:3], 0, s[88:89]
	s_add_i32 m0, s24, 0x18400
	v_ashrrev_i32_e32 v5, 31, v4
	global_load_lds_dwordx4 v[2:3], off
	v_lshl_add_u64 v[2:3], v[4:5], 1, s[80:81]
	s_add_i32 m0, s24, 0x1c400
	s_nop 0
	global_load_lds_dwordx4 v[2:3], off
	v_lshl_add_u64 v[2:3], v[2:3], 0, s[84:85]
	s_add_i32 m0, s24, 0x20400
	s_nop 0
	global_load_lds_dwordx4 v[2:3], off
.LBB0_699:
	s_add_i32 s14, s72, 0xffffff80
	s_cmp_gt_i32 s14, s19
	s_cbranch_scc1 .LBB0_737
	s_mul_hi_u32 s14, s28, 0xaaaaaaab
	s_lshr_b32 s74, s14, 1
	s_mul_i32 s74, s74, 0x24000
	v_subrev_u32_e32 v0, s74, v224
	v_add_u32_e32 v6, s39, v229
	v_add_u32_e32 v0, v6, v0
	v_subrev_u32_e32 v7, s74, v225
	v_add_u32_e32 v7, v6, v7
	v_subrev_u32_e32 v8, s74, v226
	v_add_u32_e32 v8, v6, v8
	v_subrev_u32_e32 v9, s74, v227
	v_add_u32_e32 v6, v6, v9
	ds_read_b128 v[2:5], v0
	ds_read_b128 v[10:13], v0 offset:8192
	ds_read_b128 v[176:179], v7
	ds_read_b128 v[180:183], v7 offset:8192
	ds_read_b128 v[184:187], v8
	ds_read_b128 v[188:191], v8 offset:8192
	s_add_i32 s14, s72, 0xffffffbf
	s_cmp_gt_i32 s14, s36
	s_cselect_b64 s[28:29], -1, 0
	s_cmp_le_i32 s14, s36
	s_waitcnt lgkmcnt(5)
	v_mfma_f32_32x32x16_bf16 v[160:175], v[2:5], v[192:195], 0
	ds_read_b128 v[2:5], v6
	s_waitcnt lgkmcnt(5)
	v_mfma_f32_32x32x16_bf16 v[144:159], v[10:13], v[192:195], 0
	ds_read_b128 v[10:13], v6 offset:8192
	s_waitcnt lgkmcnt(5)
	v_mfma_f32_32x32x16_bf16 v[160:175], v[176:179], v[196:199], v[160:175]
	v_xor_b32_e32 v0, 0x80, v0
	ds_read_b128 v[176:179], v0
	s_waitcnt lgkmcnt(5)
	v_mfma_f32_32x32x16_bf16 v[144:159], v[180:183], v[196:199], v[144:159]
	ds_read_b128 v[180:183], v0 offset:8192
	s_waitcnt lgkmcnt(5)
	v_mfma_f32_32x32x16_bf16 v[160:175], v[184:187], v[200:203], v[160:175]
	v_xor_b32_e32 v7, 0x80, v7
	ds_read_b128 v[184:187], v7
	s_waitcnt lgkmcnt(5)
	v_mfma_f32_32x32x16_bf16 v[144:159], v[188:191], v[200:203], v[144:159]
	ds_read_b128 v[188:191], v7 offset:8192
	s_waitcnt lgkmcnt(5)
	v_mfma_f32_32x32x16_bf16 v[160:175], v[2:5], v[204:207], v[160:175]
	v_xor_b32_e32 v8, 0x80, v8
	ds_read_b128 v[2:5], v8
	s_waitcnt lgkmcnt(5)
	v_mfma_f32_32x32x16_bf16 v[144:159], v[10:13], v[204:207], v[144:159]
	ds_read_b128 v[10:13], v8 offset:8192
	s_waitcnt lgkmcnt(5)
	v_mfma_f32_32x32x16_bf16 v[160:175], v[176:179], v[208:211], v[160:175]
	v_xor_b32_e32 v6, 0x80, v6
	ds_read_b128 v[176:179], v6
	s_waitcnt lgkmcnt(5)
	v_mfma_f32_32x32x16_bf16 v[144:159], v[180:183], v[208:211], v[144:159]
	ds_read_b128 v[180:183], v6 offset:8192
	s_waitcnt lgkmcnt(5)
	v_mfma_f32_32x32x16_bf16 v[160:175], v[184:187], v[212:215], v[160:175]
	s_waitcnt lgkmcnt(4)
	v_mfma_f32_32x32x16_bf16 v[144:159], v[188:191], v[212:215], v[144:159]
	s_waitcnt lgkmcnt(3)
	v_mfma_f32_32x32x16_bf16 v[160:175], v[2:5], v[216:219], v[160:175]
	s_waitcnt lgkmcnt(2)
	v_mfma_f32_32x32x16_bf16 v[144:159], v[10:13], v[216:219], v[144:159]
	s_waitcnt lgkmcnt(1)
	v_mfma_f32_32x32x16_bf16 v[160:175], v[176:179], v[220:223], v[160:175]
	s_waitcnt lgkmcnt(0)
	s_nop 0
	v_mfma_f32_32x32x16_bf16 v[144:159], v[180:183], v[220:223], v[144:159]
	s_cbranch_scc1 .LBB0_734
; #define LAS __attribute__((address_space(3)))
; __device__ __forceinline__ void bias_mask_tile(f32x16& p0, f32x16& p1, int dq, const LAS float* bt) {
;     const float NEG = -__builtin_inff();
;     const LAS float* b = bt + BT_PAD + dq - 59;
; #pragma unroll
;     for (int r = 0; r < 16; ++r) {
;         const int c = (r & 3) + 8 * (r >> 2);
;         const float v0 = b[59 - c], v1 = b[59 - c - 32];
;         p0[r] = (dq - c) >= 0 ? p0[r] + v0 : NEG;
;         p1[r] = (dq - c - 32) >= 0 ? p1[r] + v1 : NEG;
;     }
; }
	v_add_u32_e32 v232, 0x28494, v230
	ds_read2_b32 v[176:177], v232 offset0:59 offset1:58
	ds_read2_b32 v[178:179], v232 offset0:57 offset1:56
	ds_read2_b32 v[180:181], v232 offset0:51 offset1:50
	ds_read2_b32 v[182:183], v232 offset0:49 offset1:48
	ds_read2_b32 v[184:185], v232 offset0:43 offset1:42
	ds_read2_b32 v[186:187], v232 offset0:41 offset1:40
	ds_read2_b32 v[188:189], v232 offset0:35 offset1:34
	ds_read2_b32 v[190:191], v232 offset0:33 offset1:32
	ds_read2_b32 v[2:3], v232 offset0:27 offset1:26
	ds_read2_b32 v[4:5], v232 offset0:25 offset1:24
	ds_read2_b32 v[6:7], v232 offset0:19 offset1:18
	ds_read2_b32 v[8:9], v232 offset0:17 offset1:16
	ds_read2_b32 v[10:11], v232 offset0:11 offset1:10
	ds_read2_b32 v[12:13], v232 offset0:9 offset1:8
	ds_read2_b32 v[14:15], v232 offset0:3 offset1:2
	ds_read_b32 v0, v232 offset:4
	ds_read_b32 v232, v232
	s_waitcnt lgkmcnt(0)
	v_add_f32_e32 v176, v160, v176
	v_cmp_lt_i32_e64 s[14:15], -1, v228
	v_add_f32_e32 v177, v161, v177
	v_cmp_lt_i32_e64 vcc, 0, v228
	v_add_f32_e32 v178, v162, v178
	v_cmp_lt_i32_e64 s[90:91], 1, v228
	v_cndmask_b32_e64 v160, v239, v176, s[14:15]
	v_add_f32_e32 v179, v163, v179
	v_cmp_lt_i32_e64 s[98:99], 2, v228
	v_cndmask_b32_e64 v161, v239, v177, vcc
	v_add_f32_e32 v180, v164, v180
	v_cmp_lt_i32_e64 s[14:15], 7, v228
	v_cndmask_b32_e64 v162, v239, v178, s[90:91]
	v_add_f32_e32 v181, v165, v181
	v_cmp_lt_i32_e64 vcc, 8, v228
	v_cndmask_b32_e64 v163, v239, v179, s[98:99]
	v_add_f32_e32 v182, v166, v182
	v_cmp_lt_i32_e64 s[90:91], 9, v228
	v_cndmask_b32_e64 v164, v239, v180, s[14:15]
	v_add_f32_e32 v183, v167, v183
	v_cmp_lt_i32_e64 s[98:99], 10, v228
	v_cndmask_b32_e64 v165, v239, v181, vcc
	v_add_f32_e32 v184, v168, v184
	v_cmp_lt_i32_e64 s[14:15], 15, v228
	v_cndmask_b32_e64 v166, v239, v182, s[90:91]
	v_add_f32_e32 v185, v169, v185
	v_cmp_lt_i32_e64 vcc, 16, v228
	v_cndmask_b32_e64 v167, v239, v183, s[98:99]
	v_add_f32_e32 v186, v170, v186
	v_cmp_lt_i32_e64 s[90:91], 17, v228
	v_cndmask_b32_e64 v168, v239, v184, s[14:15]
	v_add_f32_e32 v187, v171, v187
	v_cmp_lt_i32_e64 s[98:99], 18, v228
	v_cndmask_b32_e64 v169, v239, v185, vcc
	v_add_f32_e32 v188, v172, v188
	v_cmp_lt_i32_e64 s[14:15], 23, v228
	v_cndmask_b32_e64 v170, v239, v186, s[90:91]
	v_add_f32_e32 v189, v173, v189
	v_cmp_lt_i32_e64 vcc, 24, v228
	v_cndmask_b32_e64 v171, v239, v187, s[98:99]
	v_add_f32_e32 v190, v174, v190
	v_cmp_lt_i32_e64 s[90:91], 25, v228
	v_cndmask_b32_e64 v172, v239, v188, s[14:15]
	v_add_f32_e32 v191, v175, v191
	v_cmp_lt_i32_e64 s[98:99], 26, v228
	v_cndmask_b32_e64 v173, v239, v189, vcc
	v_add_f32_e32 v2, v144, v2
	v_cmp_lt_i32_e64 s[14:15], 31, v228
	v_cndmask_b32_e64 v174, v239, v190, s[90:91]
	v_add_f32_e32 v3, v145, v3
	v_cmp_lt_i32_e64 vcc, 32, v228
	v_cndmask_b32_e64 v175, v239, v191, s[98:99]
	v_add_f32_e32 v4, v146, v4
	v_cmp_lt_i32_e64 s[90:91], 33, v228
	v_cndmask_b32_e64 v144, v239, v2, s[14:15]
	v_add_f32_e32 v5, v147, v5
	v_cmp_lt_i32_e64 s[98:99], 34, v228
	v_cndmask_b32_e64 v145, v239, v3, vcc
	v_add_f32_e32 v6, v148, v6
	v_cmp_lt_i32_e64 s[14:15], 39, v228
	v_cndmask_b32_e64 v146, v239, v4, s[90:91]
	v_add_f32_e32 v7, v149, v7
	v_cmp_lt_i32_e64 vcc, 40, v228
	v_cndmask_b32_e64 v147, v239, v5, s[98:99]
	v_add_f32_e32 v8, v150, v8
	v_cmp_lt_i32_e64 s[90:91], 41, v228
	v_cndmask_b32_e64 v148, v239, v6, s[14:15]
	v_add_f32_e32 v9, v151, v9
	v_cmp_lt_i32_e64 s[98:99], 42, v228
	v_cndmask_b32_e64 v149, v239, v7, vcc
	v_add_f32_e32 v10, v152, v10
	v_cmp_lt_i32_e64 s[14:15], 47, v228
	v_cndmask_b32_e64 v150, v239, v8, s[90:91]
	v_add_f32_e32 v11, v153, v11
	v_cmp_lt_i32_e64 vcc, 48, v228
	v_cndmask_b32_e64 v151, v239, v9, s[98:99]
	v_add_f32_e32 v12, v154, v12
	v_cmp_lt_i32_e64 s[90:91], 49, v228
	v_cndmask_b32_e64 v152, v239, v10, s[14:15]
	v_add_f32_e32 v13, v155, v13
	v_cmp_lt_i32_e64 s[98:99], 50, v228
	v_cndmask_b32_e64 v153, v239, v11, vcc
	v_add_f32_e32 v14, v156, v14
	v_cmp_lt_i32_e64 s[14:15], 55, v228
	v_cndmask_b32_e64 v154, v239, v12, s[90:91]
	v_add_f32_e32 v15, v157, v15
	v_cmp_lt_i32_e64 vcc, 56, v228
	v_cndmask_b32_e64 v155, v239, v13, s[98:99]
	v_add_f32_e32 v0, v158, v0
	v_cmp_lt_i32_e64 s[90:91], 57, v228
	v_cndmask_b32_e64 v156, v239, v14, s[14:15]
	v_add_f32_e32 v232, v159, v232
	v_cmp_lt_i32_e64 s[98:99], 58, v228
	v_cndmask_b32_e64 v157, v239, v15, vcc
	s_nop 0
	v_cndmask_b32_e64 v158, v239, v0, s[90:91]
	v_cndmask_b32_e64 v159, v239, v232, s[98:99]
